# EpiB row-stat loads hoisted before K loop (G1,G3,G5); first-iteration vmcnt waits relaxed in G1,G5 so tile stores stay in flight
# baseline (speedup 1.0000x reference)
.LBB0_130:
	s_ashr_i32 s23, s22, 31
	s_lshl_b64 s[24:25], s[22:23], 19
	s_add_u32 s24, s36, s24
	s_addc_u32 s25, s37, s25
	s_and_b64 s[26:27], s[6:7], exec
	s_cselect_b32 s23, s25, s9
	s_cselect_b32 s58, s24, s8
	s_ashr_i32 s21, s20, 31
	s_lshl_b64 s[26:27], s[20:21], 19
	s_add_u32 s26, s38, s26
	s_addc_u32 s27, s39, s27
	s_and_b64 s[28:29], s[6:7], exec
	s_cselect_b32 s21, s27, s11
	s_cselect_b32 s59, s26, s10
	s_add_u32 s68, s58, 0x80
	s_addc_u32 s69, s23, 0
	s_add_u32 s28, s8, 0x40080
	s_addc_u32 s29, s9, 0
	s_add_u32 s70, s10, 0x100
	v_mov_b32_e32 v2, 0
	v_lshl_add_u64 v[142:143], s[28:29], 0, v[138:139]
	v_lshl_add_u64 v[144:145], s[28:29], 0, v[140:141]
	s_addc_u32 s71, s11, 0
	s_mov_b32 s72, -2
	s_mov_b64 s[10:11], 0
	v_mov_b32_e32 v3, v2
	v_mov_b32_e32 v4, v2
	v_mov_b32_e32 v5, v2
	v_mov_b32_e32 v6, v2
	v_mov_b32_e32 v7, v2
	v_mov_b32_e32 v8, v2
	v_mov_b32_e32 v9, v2
	v_mov_b32_e32 v18, v2
	v_mov_b32_e32 v19, v2
	v_mov_b32_e32 v20, v2
	v_mov_b32_e32 v21, v2
	v_mov_b32_e32 v22, v2
	v_mov_b32_e32 v23, v2
	v_mov_b32_e32 v24, v2
	v_mov_b32_e32 v25, v2
	v_mov_b32_e32 v34, v2
	v_mov_b32_e32 v35, v2
	v_mov_b32_e32 v36, v2
	v_mov_b32_e32 v37, v2
	v_mov_b32_e32 v38, v2
	v_mov_b32_e32 v39, v2
	v_mov_b32_e32 v40, v2
	v_mov_b32_e32 v41, v2
	v_mov_b32_e32 v50, v2
	v_mov_b32_e32 v51, v2
	v_mov_b32_e32 v52, v2
	v_mov_b32_e32 v53, v2
	v_mov_b32_e32 v54, v2
	v_mov_b32_e32 v55, v2
	v_mov_b32_e32 v56, v2
	v_mov_b32_e32 v57, v2
	v_mov_b32_e32 v10, v2
	v_mov_b32_e32 v11, v2
	v_mov_b32_e32 v12, v2
	v_mov_b32_e32 v13, v2
	v_mov_b32_e32 v14, v2
	v_mov_b32_e32 v15, v2
	v_mov_b32_e32 v16, v2
	v_mov_b32_e32 v17, v2
	v_mov_b32_e32 v26, v2
	v_mov_b32_e32 v27, v2
	v_mov_b32_e32 v28, v2
	v_mov_b32_e32 v29, v2
	v_mov_b32_e32 v30, v2
	v_mov_b32_e32 v31, v2
	v_mov_b32_e32 v32, v2
	v_mov_b32_e32 v33, v2
	v_mov_b32_e32 v42, v2
	v_mov_b32_e32 v43, v2
	v_mov_b32_e32 v44, v2
	v_mov_b32_e32 v45, v2
	v_mov_b32_e32 v46, v2
	v_mov_b32_e32 v47, v2
	v_mov_b32_e32 v48, v2
	v_mov_b32_e32 v49, v2
	v_mov_b32_e32 v58, v2
	v_mov_b32_e32 v59, v2
	v_mov_b32_e32 v60, v2
	v_mov_b32_e32 v61, v2
	v_mov_b32_e32 v62, v2
	v_mov_b32_e32 v63, v2
	v_mov_b32_e32 v64, v2
	v_mov_b32_e32 v65, v2
	v_mov_b32_e32 v66, v2
	v_mov_b32_e32 v67, v2
	v_mov_b32_e32 v68, v2
	v_mov_b32_e32 v69, v2
	v_mov_b32_e32 v70, v2
	v_mov_b32_e32 v71, v2
	v_mov_b32_e32 v72, v2
	v_mov_b32_e32 v73, v2
	v_mov_b32_e32 v82, v2
	v_mov_b32_e32 v83, v2
	v_mov_b32_e32 v84, v2
	v_mov_b32_e32 v85, v2
	v_mov_b32_e32 v86, v2
	v_mov_b32_e32 v87, v2
	v_mov_b32_e32 v88, v2
	v_mov_b32_e32 v89, v2
	v_mov_b32_e32 v98, v2
	v_mov_b32_e32 v99, v2
	v_mov_b32_e32 v100, v2
	v_mov_b32_e32 v101, v2
	v_mov_b32_e32 v102, v2
	v_mov_b32_e32 v103, v2
	v_mov_b32_e32 v104, v2
	v_mov_b32_e32 v105, v2
	v_mov_b32_e32 v114, v2
	v_mov_b32_e32 v115, v2
	v_mov_b32_e32 v116, v2
	v_mov_b32_e32 v117, v2
	v_mov_b32_e32 v118, v2
	v_mov_b32_e32 v119, v2
	v_mov_b32_e32 v120, v2
	v_mov_b32_e32 v121, v2
	v_mov_b32_e32 v74, v2
	v_mov_b32_e32 v75, v2
	v_mov_b32_e32 v76, v2
	v_mov_b32_e32 v77, v2
	v_mov_b32_e32 v78, v2
	v_mov_b32_e32 v79, v2
	v_mov_b32_e32 v80, v2
	v_mov_b32_e32 v81, v2
	v_mov_b32_e32 v90, v2
	v_mov_b32_e32 v91, v2
	v_mov_b32_e32 v92, v2
	v_mov_b32_e32 v93, v2
	v_mov_b32_e32 v94, v2
	v_mov_b32_e32 v95, v2
	v_mov_b32_e32 v96, v2
	v_mov_b32_e32 v97, v2
	v_mov_b32_e32 v106, v2
	v_mov_b32_e32 v107, v2
	v_mov_b32_e32 v108, v2
	v_mov_b32_e32 v109, v2
	v_mov_b32_e32 v110, v2
	v_mov_b32_e32 v111, v2
	v_mov_b32_e32 v112, v2
	v_mov_b32_e32 v113, v2
	v_mov_b32_e32 v122, v2
	v_mov_b32_e32 v123, v2
	v_mov_b32_e32 v124, v2
	v_mov_b32_e32 v125, v2
	v_mov_b32_e32 v126, v2
	v_mov_b32_e32 v127, v2
	v_mov_b32_e32 v128, v2
	v_mov_b32_e32 v129, v2
	v_lshl_add_u32 v252, s57, 8, v147
	v_ashrrev_i32_e32 v253, 31, v252
	v_lshl_add_u64 v[252:253], v[252:253], 2, s[16:17]
	global_load_dword v234, v[252:253], off
	global_load_dword v235, v[252:253], off offset:64
	global_load_dword v236, v[252:253], off offset:128
	global_load_dword v237, v[252:253], off offset:192
	global_load_dword v242, v[252:253], off offset:512
	global_load_dword v243, v[252:253], off offset:576
	global_load_dword v244, v[252:253], off offset:640
	global_load_dword v254, v[252:253], off offset:704
.LBB0_131:
	s_add_u32 s28, s8, s10
	s_addc_u32 s29, s9, s11
	s_add_u32 s34, s28, 0x100
	s_addc_u32 s35, s29, 0
	s_add_u32 s30, s70, s10
	s_addc_u32 s31, s71, s11
	s_add_u32 s28, s28, 0x180
	s_addc_u32 s29, s29, 0
	s_add_i32 s73, 0, 0x10000
	s_add_i32 s76, 0, 0x14000
	v_add_u32_e32 v146, s73, v166
	ds_read_b128 v[148:151], v146
	ds_read_b128 v[152:155], v146 offset:1024
	ds_read_b128 v[156:159], v146 offset:2048
	ds_read_b128 v[160:163], v146 offset:3072
	v_add_u32_e32 v146, s76, v166
	ds_read_b128 v[172:175], v146
	ds_read_b128 v[176:179], v146 offset:1024
	ds_read_b128 v[180:183], v146 offset:2048
	ds_read_b128 v[184:187], v146 offset:3072
	s_cmpk_eq_i32 s10, 0x700
	s_cselect_b32 s29, s69, s29
	s_cselect_b32 s28, s68, s28
	s_cselect_b32 s31, s21, s31
	s_cselect_b32 s30, s59, s30
	s_cselect_b32 s35, s23, s35
	s_cselect_b32 s34, s58, s34
	v_lshl_add_u64 v[164:165], v[142:143], 0, s[10:11]
	s_add_i32 m0, s41, 0xc000
	ds_read_b128 v[188:191], v171
	ds_read_b128 v[202:205], v171 offset:1024
	ds_read_b128 v[206:209], v171 offset:2048
	ds_read_b128 v[210:213], v171 offset:3072
	ds_read_b128 v[214:217], v171 offset:4096
	ds_read_b128 v[218:221], v171 offset:5120
	ds_read_b128 v[222:225], v171 offset:6144
	ds_read_b128 v[226:229], v171 offset:7168
	global_load_lds_dwordx4 v[164:165], off
	v_lshl_add_u64 v[164:165], v[144:145], 0, s[10:11]
	s_add_i32 m0, s41, 0xe000
	s_nop 0
	global_load_lds_dwordx4 v[164:165], off
	s_cmp_lg_u32 s72, -2
	s_cbranch_scc1 .Lg1wa_norm
	s_cmp_eq_u32 s55, 1
	s_cbranch_scc1 .Lg1wa_first
	s_waitcnt vmcnt(32)
	s_branch .Lg1wa_done
.Lg1wa_first:
	s_waitcnt vmcnt(16)
	s_branch .Lg1wa_done
.Lg1wa_norm:
	s_waitcnt vmcnt(8)
.Lg1wa_done:
	s_waitcnt lgkmcnt(0)
	s_barrier
	s_setprio 1
	s_waitcnt lgkmcnt(0)
	v_mfma_f32_16x16x32_bf16 v[126:129], v[148:151], v[188:191], v[126:129]
	v_mfma_f32_16x16x32_bf16 v[122:125], v[156:159], v[188:191], v[122:125]
	v_mfma_f32_16x16x32_bf16 v[110:113], v[148:151], v[206:209], v[110:113]
	v_mfma_f32_16x16x32_bf16 v[106:109], v[156:159], v[206:209], v[106:109]
	v_mfma_f32_16x16x32_bf16 v[94:97], v[148:151], v[214:217], v[94:97]
	v_mfma_f32_16x16x32_bf16 v[90:93], v[156:159], v[214:217], v[90:93]
	v_mfma_f32_16x16x32_bf16 v[78:81], v[148:151], v[222:225], v[78:81]
	v_mfma_f32_16x16x32_bf16 v[74:77], v[156:159], v[222:225], v[74:77]
	v_mfma_f32_16x16x32_bf16 v[126:129], v[152:155], v[202:205], v[126:129]
	v_mfma_f32_16x16x32_bf16 v[122:125], v[160:163], v[202:205], v[122:125]
	v_mfma_f32_16x16x32_bf16 v[110:113], v[152:155], v[210:213], v[110:113]
	v_mfma_f32_16x16x32_bf16 v[106:109], v[160:163], v[210:213], v[106:109]
	v_mfma_f32_16x16x32_bf16 v[94:97], v[152:155], v[218:221], v[94:97]
	v_mfma_f32_16x16x32_bf16 v[90:93], v[160:163], v[218:221], v[90:93]
	v_mfma_f32_16x16x32_bf16 v[78:81], v[152:155], v[226:229], v[78:81]
	v_mfma_f32_16x16x32_bf16 v[74:77], v[160:163], v[226:229], v[74:77]
	s_setprio 0
	s_setprio 1
	v_mfma_f32_16x16x32_bf16 v[118:121], v[172:175], v[188:191], v[118:121]
	v_mfma_f32_16x16x32_bf16 v[114:117], v[180:183], v[188:191], v[114:117]
	v_mfma_f32_16x16x32_bf16 v[102:105], v[172:175], v[206:209], v[102:105]
	v_mfma_f32_16x16x32_bf16 v[98:101], v[180:183], v[206:209], v[98:101]
	v_mfma_f32_16x16x32_bf16 v[86:89], v[172:175], v[214:217], v[86:89]
	v_mfma_f32_16x16x32_bf16 v[82:85], v[180:183], v[214:217], v[82:85]
	v_mfma_f32_16x16x32_bf16 v[70:73], v[172:175], v[222:225], v[70:73]
	v_mfma_f32_16x16x32_bf16 v[66:69], v[180:183], v[222:225], v[66:69]
	v_mfma_f32_16x16x32_bf16 v[118:121], v[176:179], v[202:205], v[118:121]
	v_mfma_f32_16x16x32_bf16 v[114:117], v[184:187], v[202:205], v[114:117]
	v_mfma_f32_16x16x32_bf16 v[102:105], v[176:179], v[210:213], v[102:105]
	v_mfma_f32_16x16x32_bf16 v[98:101], v[184:187], v[210:213], v[98:101]
	v_mfma_f32_16x16x32_bf16 v[86:89], v[176:179], v[218:221], v[86:89]
	v_mfma_f32_16x16x32_bf16 v[82:85], v[184:187], v[218:221], v[82:85]
	v_mfma_f32_16x16x32_bf16 v[70:73], v[176:179], v[226:229], v[70:73]
	v_mfma_f32_16x16x32_bf16 v[66:69], v[184:187], v[226:229], v[66:69]
	s_setprio 0
	s_barrier
	s_add_i32 s73, s73, s40
	v_lshl_add_u64 v[164:165], s[30:31], 0, v[134:135]
	s_mov_b32 m0, s73
	ds_read_b128 v[188:191], v171 offset:16384
	ds_read_b128 v[202:205], v171 offset:17408
	ds_read_b128 v[206:209], v171 offset:18432
	ds_read_b128 v[210:213], v171 offset:19456
	ds_read_b128 v[214:217], v171 offset:20480
	ds_read_b128 v[218:221], v171 offset:21504
	ds_read_b128 v[222:225], v171 offset:22528
	ds_read_b128 v[226:229], v171 offset:23552
	global_load_lds_dwordx4 v[164:165], off
	s_add_i32 m0, s73, 0x2000
	s_add_u32 s74, s30, 0x40000
	v_lshl_add_u64 v[192:193], s[30:31], 0, v[130:131]
	s_addc_u32 s75, s31, 0
	s_add_i32 s73, s76, s40
	global_load_lds_dwordx4 v[192:193], off
	v_lshl_add_u64 v[194:195], s[74:75], 0, v[134:135]
	s_mov_b32 m0, s73
	s_nop 0
	global_load_lds_dwordx4 v[194:195], off
	v_lshl_add_u64 v[194:195], s[74:75], 0, v[130:131]
	s_add_i32 m0, s73, 0x2000
	s_nop 0
	global_load_lds_dwordx4 v[194:195], off
	v_lshl_add_u64 v[194:195], s[34:35], 0, v[136:137]
	s_mov_b32 m0, s41
	s_nop 0
	global_load_lds_dwordx4 v[194:195], off
	v_lshl_add_u64 v[194:195], s[34:35], 0, v[132:133]
	s_mov_b32 m0, s42
	s_nop 0
	global_load_lds_dwordx4 v[194:195], off
	s_cmp_lg_u32 s72, -2
	s_cbranch_scc1 .Lg1wb_norm
	s_cmp_eq_u32 s55, 1
	s_cbranch_scc1 .Lg1wb_first
	s_waitcnt vmcnt(32)
	s_branch .Lg1wb_done

.Lg1wb_done:
	s_waitcnt lgkmcnt(0)
	s_barrier
	s_setprio 1
	s_waitcnt lgkmcnt(0)
	v_mfma_f32_16x16x32_bf16 v[62:65], v[148:151], v[188:191], v[62:65]
	v_mfma_f32_16x16x32_bf16 v[58:61], v[156:159], v[188:191], v[58:61]
	v_mfma_f32_16x16x32_bf16 v[46:49], v[148:151], v[206:209], v[46:49]
	v_mfma_f32_16x16x32_bf16 v[42:45], v[156:159], v[206:209], v[42:45]
	v_mfma_f32_16x16x32_bf16 v[30:33], v[148:151], v[214:217], v[30:33]
	v_mfma_f32_16x16x32_bf16 v[26:29], v[156:159], v[214:217], v[26:29]
	v_mfma_f32_16x16x32_bf16 v[14:17], v[148:151], v[222:225], v[14:17]
	v_mfma_f32_16x16x32_bf16 v[10:13], v[156:159], v[222:225], v[10:13]
	v_mfma_f32_16x16x32_bf16 v[62:65], v[152:155], v[202:205], v[62:65]
	v_mfma_f32_16x16x32_bf16 v[58:61], v[160:163], v[202:205], v[58:61]
	v_mfma_f32_16x16x32_bf16 v[46:49], v[152:155], v[210:213], v[46:49]
	v_mfma_f32_16x16x32_bf16 v[42:45], v[160:163], v[210:213], v[42:45]
	v_mfma_f32_16x16x32_bf16 v[30:33], v[152:155], v[218:221], v[30:33]
	v_mfma_f32_16x16x32_bf16 v[26:29], v[160:163], v[218:221], v[26:29]
	v_mfma_f32_16x16x32_bf16 v[14:17], v[152:155], v[226:229], v[14:17]
	v_mfma_f32_16x16x32_bf16 v[10:13], v[160:163], v[226:229], v[10:13]
	s_setprio 0
	s_setprio 1
	v_mfma_f32_16x16x32_bf16 v[54:57], v[172:175], v[188:191], v[54:57]
	v_mfma_f32_16x16x32_bf16 v[50:53], v[180:183], v[188:191], v[50:53]
	v_mfma_f32_16x16x32_bf16 v[38:41], v[172:175], v[206:209], v[38:41]
	v_mfma_f32_16x16x32_bf16 v[34:37], v[180:183], v[206:209], v[34:37]
	v_mfma_f32_16x16x32_bf16 v[22:25], v[172:175], v[214:217], v[22:25]
	v_mfma_f32_16x16x32_bf16 v[18:21], v[180:183], v[214:217], v[18:21]
	v_mfma_f32_16x16x32_bf16 v[6:9], v[172:175], v[222:225], v[6:9]
	v_mfma_f32_16x16x32_bf16 v[2:5], v[180:183], v[222:225], v[2:5]
	v_mfma_f32_16x16x32_bf16 v[54:57], v[176:179], v[202:205], v[54:57]
	v_mfma_f32_16x16x32_bf16 v[50:53], v[184:187], v[202:205], v[50:53]
	v_mfma_f32_16x16x32_bf16 v[38:41], v[176:179], v[210:213], v[38:41]
	v_mfma_f32_16x16x32_bf16 v[34:37], v[184:187], v[210:213], v[34:37]
	v_mfma_f32_16x16x32_bf16 v[22:25], v[176:179], v[218:221], v[22:25]
	v_mfma_f32_16x16x32_bf16 v[18:21], v[184:187], v[218:221], v[18:21]
	v_mfma_f32_16x16x32_bf16 v[6:9], v[176:179], v[226:229], v[6:9]
	v_mfma_f32_16x16x32_bf16 v[2:5], v[184:187], v[226:229], v[2:5]
	s_setprio 0
	s_barrier
	s_add_i32 s73, 0, 0x18000
	v_add_u32_e32 v146, s73, v166
	s_add_i32 s74, 0, 0x1c000
	ds_read_b128 v[148:151], v146
	ds_read_b128 v[152:155], v146 offset:1024
	ds_read_b128 v[156:159], v146 offset:2048
	ds_read_b128 v[160:163], v146 offset:3072
	v_add_u32_e32 v146, s74, v166
	ds_read_b128 v[172:175], v146
	ds_read_b128 v[176:179], v146 offset:1024
	ds_read_b128 v[180:183], v146 offset:2048
	ds_read_b128 v[184:187], v146 offset:3072
	s_add_u32 s34, s34, 0x40000
	s_addc_u32 s35, s35, 0
	s_mov_b32 m0, s43
	v_lshl_add_u64 v[194:195], s[34:35], 0, v[136:137]
	ds_read_b128 v[188:191], v171 offset:32768
	ds_read_b128 v[202:205], v171 offset:33792
	ds_read_b128 v[206:209], v171 offset:34816
	ds_read_b128 v[210:213], v171 offset:35840
	ds_read_b128 v[214:217], v171 offset:36864
	ds_read_b128 v[218:221], v171 offset:37888
	ds_read_b128 v[222:225], v171 offset:38912
	ds_read_b128 v[226:229], v171 offset:39936
	global_load_lds_dwordx4 v[194:195], off
	v_lshl_add_u64 v[194:195], s[34:35], 0, v[132:133]
	s_mov_b32 m0, s44
	s_nop 0
	global_load_lds_dwordx4 v[194:195], off
	s_waitcnt vmcnt(8)
	s_waitcnt lgkmcnt(0)
	s_barrier
	s_setprio 1
	s_waitcnt lgkmcnt(0)
	v_mfma_f32_16x16x32_bf16 v[126:129], v[148:151], v[188:191], v[126:129]
	v_mfma_f32_16x16x32_bf16 v[122:125], v[156:159], v[188:191], v[122:125]
	v_mfma_f32_16x16x32_bf16 v[110:113], v[148:151], v[206:209], v[110:113]
	v_mfma_f32_16x16x32_bf16 v[106:109], v[156:159], v[206:209], v[106:109]
	v_mfma_f32_16x16x32_bf16 v[94:97], v[148:151], v[214:217], v[94:97]
	v_mfma_f32_16x16x32_bf16 v[90:93], v[156:159], v[214:217], v[90:93]
	v_mfma_f32_16x16x32_bf16 v[78:81], v[148:151], v[222:225], v[78:81]
	v_mfma_f32_16x16x32_bf16 v[74:77], v[156:159], v[222:225], v[74:77]
	v_mfma_f32_16x16x32_bf16 v[126:129], v[152:155], v[202:205], v[126:129]
	v_mfma_f32_16x16x32_bf16 v[122:125], v[160:163], v[202:205], v[122:125]
	v_mfma_f32_16x16x32_bf16 v[110:113], v[152:155], v[210:213], v[110:113]
	v_mfma_f32_16x16x32_bf16 v[106:109], v[160:163], v[210:213], v[106:109]
	v_mfma_f32_16x16x32_bf16 v[94:97], v[152:155], v[218:221], v[94:97]
	v_mfma_f32_16x16x32_bf16 v[90:93], v[160:163], v[218:221], v[90:93]
	v_mfma_f32_16x16x32_bf16 v[78:81], v[152:155], v[226:229], v[78:81]
	v_mfma_f32_16x16x32_bf16 v[74:77], v[160:163], v[226:229], v[74:77]
	s_setprio 0
	s_setprio 1
	v_mfma_f32_16x16x32_bf16 v[118:121], v[172:175], v[188:191], v[118:121]
	v_mfma_f32_16x16x32_bf16 v[114:117], v[180:183], v[188:191], v[114:117]
	v_mfma_f32_16x16x32_bf16 v[102:105], v[172:175], v[206:209], v[102:105]
	v_mfma_f32_16x16x32_bf16 v[98:101], v[180:183], v[206:209], v[98:101]
	v_mfma_f32_16x16x32_bf16 v[86:89], v[172:175], v[214:217], v[86:89]
	v_mfma_f32_16x16x32_bf16 v[82:85], v[180:183], v[214:217], v[82:85]
	v_mfma_f32_16x16x32_bf16 v[70:73], v[172:175], v[222:225], v[70:73]
	v_mfma_f32_16x16x32_bf16 v[66:69], v[180:183], v[222:225], v[66:69]
	v_mfma_f32_16x16x32_bf16 v[118:121], v[176:179], v[202:205], v[118:121]
	v_mfma_f32_16x16x32_bf16 v[114:117], v[184:187], v[202:205], v[114:117]
	v_mfma_f32_16x16x32_bf16 v[102:105], v[176:179], v[210:213], v[102:105]
	v_mfma_f32_16x16x32_bf16 v[98:101], v[184:187], v[210:213], v[98:101]
	v_mfma_f32_16x16x32_bf16 v[86:89], v[176:179], v[218:221], v[86:89]
	v_mfma_f32_16x16x32_bf16 v[82:85], v[184:187], v[218:221], v[82:85]
	v_mfma_f32_16x16x32_bf16 v[70:73], v[176:179], v[226:229], v[70:73]
	v_mfma_f32_16x16x32_bf16 v[66:69], v[184:187], v[226:229], v[66:69]
	s_setprio 0
	s_barrier
	s_add_i32 s34, s73, s40
	v_lshl_add_u64 v[164:165], v[164:165], 0, s[90:91]
	s_mov_b32 m0, s34
	ds_read_b128 v[188:191], v171 offset:49152
	ds_read_b128 v[202:205], v171 offset:50176
	ds_read_b128 v[206:209], v171 offset:51200
	ds_read_b128 v[210:213], v171 offset:52224
	ds_read_b128 v[214:217], v171 offset:53248
	ds_read_b128 v[218:221], v171 offset:54272
	ds_read_b128 v[222:225], v171 offset:55296
	ds_read_b128 v[226:229], v171 offset:56320
	global_load_lds_dwordx4 v[164:165], off
	s_add_i32 m0, s34, 0x2000
	s_add_u32 s30, s30, 0x40080
	v_lshl_add_u64 v[164:165], v[192:193], 0, s[90:91]
	s_addc_u32 s31, s31, 0
	s_add_i32 s34, s74, s40
	global_load_lds_dwordx4 v[164:165], off
	v_lshl_add_u64 v[164:165], s[30:31], 0, v[134:135]
	s_mov_b32 m0, s34
	s_nop 0
	global_load_lds_dwordx4 v[164:165], off
	v_lshl_add_u64 v[164:165], s[30:31], 0, v[130:131]
	s_add_i32 m0, s34, 0x2000
	s_nop 0
	global_load_lds_dwordx4 v[164:165], off
	v_lshl_add_u64 v[164:165], s[28:29], 0, v[136:137]
	s_mov_b32 m0, s45
	s_nop 0
	global_load_lds_dwordx4 v[164:165], off
	v_lshl_add_u64 v[164:165], s[28:29], 0, v[132:133]
	s_mov_b32 m0, s51
	s_nop 0
	global_load_lds_dwordx4 v[164:165], off
	s_waitcnt vmcnt(8)
	s_waitcnt lgkmcnt(0)
	s_barrier
	s_setprio 1
	s_waitcnt lgkmcnt(0)
	v_mfma_f32_16x16x32_bf16 v[62:65], v[148:151], v[188:191], v[62:65]
	v_mfma_f32_16x16x32_bf16 v[58:61], v[156:159], v[188:191], v[58:61]
	v_mfma_f32_16x16x32_bf16 v[46:49], v[148:151], v[206:209], v[46:49]
	v_mfma_f32_16x16x32_bf16 v[42:45], v[156:159], v[206:209], v[42:45]
	v_mfma_f32_16x16x32_bf16 v[30:33], v[148:151], v[214:217], v[30:33]
	v_mfma_f32_16x16x32_bf16 v[26:29], v[156:159], v[214:217], v[26:29]
	v_mfma_f32_16x16x32_bf16 v[14:17], v[148:151], v[222:225], v[14:17]
	v_mfma_f32_16x16x32_bf16 v[10:13], v[156:159], v[222:225], v[10:13]
	v_mfma_f32_16x16x32_bf16 v[62:65], v[152:155], v[202:205], v[62:65]
	v_mfma_f32_16x16x32_bf16 v[58:61], v[160:163], v[202:205], v[58:61]
	v_mfma_f32_16x16x32_bf16 v[46:49], v[152:155], v[210:213], v[46:49]
	v_mfma_f32_16x16x32_bf16 v[42:45], v[160:163], v[210:213], v[42:45]
	v_mfma_f32_16x16x32_bf16 v[30:33], v[152:155], v[218:221], v[30:33]
	v_mfma_f32_16x16x32_bf16 v[26:29], v[160:163], v[218:221], v[26:29]
	v_mfma_f32_16x16x32_bf16 v[14:17], v[152:155], v[226:229], v[14:17]
	v_mfma_f32_16x16x32_bf16 v[10:13], v[160:163], v[226:229], v[10:13]
	s_setprio 0
	s_setprio 1
	v_mfma_f32_16x16x32_bf16 v[54:57], v[172:175], v[188:191], v[54:57]
	v_mfma_f32_16x16x32_bf16 v[50:53], v[180:183], v[188:191], v[50:53]
	v_mfma_f32_16x16x32_bf16 v[38:41], v[172:175], v[206:209], v[38:41]
	v_mfma_f32_16x16x32_bf16 v[34:37], v[180:183], v[206:209], v[34:37]
	v_mfma_f32_16x16x32_bf16 v[22:25], v[172:175], v[214:217], v[22:25]
	v_mfma_f32_16x16x32_bf16 v[18:21], v[180:183], v[214:217], v[18:21]
	v_mfma_f32_16x16x32_bf16 v[6:9], v[172:175], v[222:225], v[6:9]
	v_mfma_f32_16x16x32_bf16 v[2:5], v[180:183], v[222:225], v[2:5]
	v_mfma_f32_16x16x32_bf16 v[54:57], v[176:179], v[202:205], v[54:57]
	v_mfma_f32_16x16x32_bf16 v[50:53], v[184:187], v[202:205], v[50:53]
	v_mfma_f32_16x16x32_bf16 v[38:41], v[176:179], v[210:213], v[38:41]
	v_mfma_f32_16x16x32_bf16 v[34:37], v[184:187], v[210:213], v[34:37]
	v_mfma_f32_16x16x32_bf16 v[22:25], v[176:179], v[218:221], v[22:25]
	v_mfma_f32_16x16x32_bf16 v[18:21], v[184:187], v[218:221], v[18:21]
	v_mfma_f32_16x16x32_bf16 v[6:9], v[176:179], v[226:229], v[6:9]
	v_mfma_f32_16x16x32_bf16 v[2:5], v[184:187], v[226:229], v[2:5]
	s_setprio 0
	s_barrier
	s_add_i32 s72, s72, 2
	s_add_u32 s10, s10, 0x100
	s_addc_u32 s11, s11, 0
	s_cmp_gt_u32 s72, 13
	s_cbranch_scc0 .LBB0_131
	s_and_b64 vcc, exec, s[18:19]
	s_cbranch_vccz .LBB0_134
	s_barrier
.LBB0_134:
	v_lshl_add_u32 v150, s57, 8, v147
	v_ashrrev_i32_e32 v151, 31, v150
	v_mov_b32_e32 v152, v234
	v_mov_b32_e32 v177, v235
	v_mov_b32_e32 v176, v236
	v_mov_b32_e32 v175, v237
	v_mov_b32_e32 v174, v242
	v_mov_b32_e32 v173, v243
	v_mov_b32_e32 v172, v244
	v_mov_b32_e32 v151, v254
	s_ashr_i32 s21, s56, 1
	s_cmp_lt_i32 s21, 2
	s_cselect_b64 s[30:31], -1, 0
	s_cmp_gt_i32 s21, 1
	s_cselect_b64 s[10:11], -1, 0
	v_mov_b32_e32 v142, 0
	s_and_b64 vcc, exec, s[10:11]
	v_mov_b32_e32 v143, v142
	v_mov_b32_e32 v148, v142
	v_mov_b32_e32 v149, v142
	v_mov_b32_e32 v144, v142
	v_mov_b32_e32 v145, v142
	v_mov_b32_e32 v146, v142
	v_mov_b32_e32 v153, v142
	s_cbranch_vccnz .LBB0_136
	v_and_b32_e32 v142, 0x7cf, v150
	v_cvt_f32_u32_e32 v149, v142
	v_mul_f32_e32 v142, v167, v149
	v_mul_f32_e32 v143, v168, v149
	v_mul_f32_e32 v146, v169, v149
	v_mul_f32_e32 v149, v170, v149
	v_fract_f32_e32 v142, v142
	v_fract_f32_e32 v143, v143
	v_fract_f32_e32 v148, v146
	v_fract_f32_e32 v149, v149
	v_sin_f32_e32 v144, v142
	v_cos_f32_e32 v142, v142
	v_sin_f32_e32 v145, v143
	v_cos_f32_e32 v143, v143
	v_sin_f32_e32 v146, v148
	v_cos_f32_e32 v148, v148
	v_sin_f32_e32 v153, v149
	v_cos_f32_e32 v149, v149
.LBB0_136:
	v_fmamk_f32 v152, v152, 0x3a800000, v233
	v_mul_f32_e32 v154, 0x4b800000, v152
	v_cmp_gt_f32_e32 vcc, s82, v152
	s_cmp_eq_u32 s21, 1
	s_cselect_b64 s[8:9], -1, 0
	v_cndmask_b32_e32 v152, v152, v154, vcc
	v_rsq_f32_e32 v152, v152
	s_mov_b64 s[28:29], -1
	v_mul_f32_e32 v154, 0x45800000, v152
	v_cndmask_b32_e32 v154, v152, v154, vcc
	v_pk_mul_f32 v[128:129], v[128:129], v[154:155] op_sel_hi:[1,0]
	v_pk_mul_f32 v[156:157], v[126:127], v[154:155] op_sel_hi:[1,0]
	v_pk_mul_f32 v[124:125], v[124:125], v[154:155] op_sel_hi:[1,0]
	v_pk_mul_f32 v[126:127], v[122:123], v[154:155] op_sel_hi:[1,0]
	s_and_b64 vcc, exec, s[10:11]
	s_cbranch_vccz .LBB0_145
	s_cmp_lt_i32 s21, 4
	s_cbranch_scc1 .LBB0_141
	s_cmp_eq_u32 s21, 4
	v_mov_b32_e32 v165, v125
	v_mov_b32_e32 v164, v124
	v_mov_b32_e32 v163, v127
	v_mov_b32_e32 v162, v126
	v_mov_b32_e32 v161, v129
	v_mov_b32_e32 v160, v128
	v_mov_b32_e32 v159, v157
	v_mov_b32_e32 v158, v156
	s_cbranch_scc0 .LBB0_140
	v_pk_mul_f32 v[160:161], v[128:129], s[92:93] op_sel_hi:[1,0]
	v_pk_mul_f32 v[158:159], v[156:157], s[92:93] op_sel_hi:[1,0]
	v_pk_mul_f32 v[164:165], v[124:125], s[92:93] op_sel_hi:[1,0]
	v_pk_mul_f32 v[162:163], v[126:127], s[92:93] op_sel_hi:[1,0]

.LBB0_674:
	s_ashr_i32 s25, s24, 31
	s_lshl_b64 s[26:27], s[24:25], 19
	s_add_u32 s26, s42, s26
	s_addc_u32 s27, s43, s27
	s_and_b64 s[28:29], s[10:11], exec
	s_cselect_b32 s25, s27, s31
	s_cselect_b32 s73, s26, s30
	s_ashr_i32 s23, s22, 31
	s_lshl_b64 s[28:29], s[22:23], 19
	s_add_u32 s28, s44, s28
	s_addc_u32 s29, s45, s29
	s_and_b64 s[36:37], s[10:11], exec
	s_cselect_b32 s23, s29, s35
	s_cselect_b32 s74, s28, s34
	s_add_u32 s75, s73, 0x80
	s_addc_u32 s76, s25, 0
	s_add_u32 s36, s30, 0x40080
	s_addc_u32 s37, s31, 0
	s_add_u32 s78, s34, 0x100
	s_waitcnt lgkmcnt(0)
	v_mov_b32_e32 v2, 0
	v_lshl_add_u64 v[144:145], s[36:37], 0, v[140:141]
	v_lshl_add_u64 v[146:147], s[36:37], 0, v[142:143]
	s_addc_u32 s85, s35, 0
	s_mov_b32 s86, -2
	s_mov_b64 s[34:35], 0
	v_mov_b32_e32 v3, v2
	v_mov_b32_e32 v4, v2
	v_mov_b32_e32 v5, v2
	v_mov_b32_e32 v6, v2
	v_mov_b32_e32 v7, v2
	v_mov_b32_e32 v8, v2
	v_mov_b32_e32 v9, v2
	v_mov_b32_e32 v18, v2
	v_mov_b32_e32 v19, v2
	v_mov_b32_e32 v20, v2
	v_mov_b32_e32 v21, v2
	v_mov_b32_e32 v22, v2
	v_mov_b32_e32 v23, v2
	v_mov_b32_e32 v24, v2
	v_mov_b32_e32 v25, v2
	v_mov_b32_e32 v34, v2
	v_mov_b32_e32 v35, v2
	v_mov_b32_e32 v36, v2
	v_mov_b32_e32 v37, v2
	v_mov_b32_e32 v38, v2
	v_mov_b32_e32 v39, v2
	v_mov_b32_e32 v40, v2
	v_mov_b32_e32 v41, v2
	v_mov_b32_e32 v50, v2
	v_mov_b32_e32 v51, v2
	v_mov_b32_e32 v52, v2
	v_mov_b32_e32 v53, v2
	v_mov_b32_e32 v54, v2
	v_mov_b32_e32 v55, v2
	v_mov_b32_e32 v56, v2
	v_mov_b32_e32 v57, v2
	v_mov_b32_e32 v10, v2
	v_mov_b32_e32 v11, v2
	v_mov_b32_e32 v12, v2
	v_mov_b32_e32 v13, v2
	v_mov_b32_e32 v14, v2
	v_mov_b32_e32 v15, v2
	v_mov_b32_e32 v16, v2
	v_mov_b32_e32 v17, v2
	v_mov_b32_e32 v26, v2
	v_mov_b32_e32 v27, v2
	v_mov_b32_e32 v28, v2
	v_mov_b32_e32 v29, v2
	v_mov_b32_e32 v30, v2
	v_mov_b32_e32 v31, v2
	v_mov_b32_e32 v32, v2
	v_mov_b32_e32 v33, v2
	v_mov_b32_e32 v42, v2
	v_mov_b32_e32 v43, v2
	v_mov_b32_e32 v44, v2
	v_mov_b32_e32 v45, v2
	v_mov_b32_e32 v46, v2
	v_mov_b32_e32 v47, v2
	v_mov_b32_e32 v48, v2
	v_mov_b32_e32 v49, v2
	v_mov_b32_e32 v58, v2
	v_mov_b32_e32 v59, v2
	v_mov_b32_e32 v60, v2
	v_mov_b32_e32 v61, v2
	v_mov_b32_e32 v62, v2
	v_mov_b32_e32 v63, v2
	v_mov_b32_e32 v64, v2
	v_mov_b32_e32 v65, v2
	v_mov_b32_e32 v66, v2
	v_mov_b32_e32 v67, v2
	v_mov_b32_e32 v68, v2
	v_mov_b32_e32 v69, v2
	v_mov_b32_e32 v70, v2
	v_mov_b32_e32 v71, v2
	v_mov_b32_e32 v72, v2
	v_mov_b32_e32 v73, v2
	v_mov_b32_e32 v82, v2
	v_mov_b32_e32 v83, v2
	v_mov_b32_e32 v84, v2
	v_mov_b32_e32 v85, v2
	v_mov_b32_e32 v86, v2
	v_mov_b32_e32 v87, v2
	v_mov_b32_e32 v88, v2
	v_mov_b32_e32 v89, v2
	v_mov_b32_e32 v98, v2
	v_mov_b32_e32 v99, v2
	v_mov_b32_e32 v100, v2
	v_mov_b32_e32 v101, v2
	v_mov_b32_e32 v102, v2
	v_mov_b32_e32 v103, v2
	v_mov_b32_e32 v104, v2
	v_mov_b32_e32 v105, v2
	v_mov_b32_e32 v114, v2
	v_mov_b32_e32 v115, v2
	v_mov_b32_e32 v116, v2
	v_mov_b32_e32 v117, v2
	v_mov_b32_e32 v118, v2
	v_mov_b32_e32 v119, v2
	v_mov_b32_e32 v120, v2
	v_mov_b32_e32 v121, v2
	v_mov_b32_e32 v74, v2
	v_mov_b32_e32 v75, v2
	v_mov_b32_e32 v76, v2
	v_mov_b32_e32 v77, v2
	v_mov_b32_e32 v78, v2
	v_mov_b32_e32 v79, v2
	v_mov_b32_e32 v80, v2
	v_mov_b32_e32 v81, v2
	v_mov_b32_e32 v90, v2
	v_mov_b32_e32 v91, v2
	v_mov_b32_e32 v92, v2
	v_mov_b32_e32 v93, v2
	v_mov_b32_e32 v94, v2
	v_mov_b32_e32 v95, v2
	v_mov_b32_e32 v96, v2
	v_mov_b32_e32 v97, v2
	v_mov_b32_e32 v106, v2
	v_mov_b32_e32 v107, v2
	v_mov_b32_e32 v108, v2
	v_mov_b32_e32 v109, v2
	v_mov_b32_e32 v110, v2
	v_mov_b32_e32 v111, v2
	v_mov_b32_e32 v112, v2
	v_mov_b32_e32 v113, v2
	v_mov_b32_e32 v122, v2
	v_mov_b32_e32 v123, v2
	v_mov_b32_e32 v124, v2
	v_mov_b32_e32 v125, v2
	v_mov_b32_e32 v126, v2
	v_mov_b32_e32 v127, v2
	v_mov_b32_e32 v128, v2
	v_mov_b32_e32 v129, v2
	v_lshl_add_u32 v252, s72, 8, v139
	v_ashrrev_i32_e32 v253, 31, v252
	v_lshl_add_u64 v[252:253], v[252:253], 2, s[16:17]
	global_load_dword v234, v[252:253], off
	global_load_dword v235, v[252:253], off offset:64
	global_load_dword v236, v[252:253], off offset:128
	global_load_dword v237, v[252:253], off offset:192
	global_load_dword v242, v[252:253], off offset:512
	global_load_dword v243, v[252:253], off offset:576
	global_load_dword v244, v[252:253], off offset:640
	global_load_dword v254, v[252:253], off offset:704

.LBB0_678:
	v_lshl_add_u32 v144, s72, 8, v139
	v_ashrrev_i32_e32 v145, 31, v144
	v_mov_b32_e32 v0, v234
	v_mov_b32_e32 v154, v235
	v_mov_b32_e32 v153, v236
	v_mov_b32_e32 v152, v237
	v_mov_b32_e32 v151, v242
	v_mov_b32_e32 v150, v243
	v_mov_b32_e32 v147, v244
	v_mov_b32_e32 v146, v254
	s_lshl_b32 s34, s71, 8
	v_lshlrev_b64 v[158:159], 11, v[144:145]
	s_ashr_i32 s35, s34, 31
	v_lshl_add_u64 v[158:159], s[14:15], 0, v[158:159]
	v_lshl_add_u64 v[158:159], s[34:35], 1, v[158:159]
	s_lshl_b32 s30, s71, 2
	s_ashr_i32 s31, s30, 31
	v_fmamk_f32 v0, v0, 0x3a800000, v233
	v_cmp_gt_f32_e32 vcc, s82, v0
	v_mul_f32_e32 v155, 0x4b800000, v0
	s_nop 0
	v_cndmask_b32_e32 v0, v0, v155, vcc
	v_rsq_f32_e32 v0, v0
	s_nop 0
	v_mul_f32_e32 v155, 0x45800000, v0
	v_cndmask_b32_e32 v156, v0, v155, vcc
	v_pk_mul_f32 v[128:129], v[128:129], v[156:157] op_sel_hi:[1,0]
	v_pk_mul_f32 v[126:127], v[126:127], v[156:157] op_sel_hi:[1,0]
	v_pk_mul_f32 v[160:161], v[124:125], v[156:157] op_sel_hi:[1,0]
	v_pk_mul_f32 v[124:125], v[122:123], v[156:157] op_sel_hi:[1,0]
	v_mul_f32_e32 v122, v127, v127
	v_mul_f32_e32 v123, v129, v129
	v_fmac_f32_e32 v122, v126, v126
	v_fmac_f32_e32 v123, v128, v128
	v_add_f32_e32 v122, v122, v123
	v_mul_f32_e32 v123, v125, v125
	v_fmac_f32_e32 v123, v124, v124
	v_add_f32_e32 v122, v123, v122
	v_mul_f32_e32 v123, v161, v161
	v_fmac_f32_e32 v123, v160, v160
	v_lshlrev_b32_e32 v0, 1, v138
	v_add_f32_e32 v155, v123, v122
	v_cvt_pk_bf16_f32 v122, v126, v127
	v_cvt_pk_bf16_f32 v123, v128, v129
	v_pk_mul_f32 v[120:121], v[120:121], v[156:157] op_sel_hi:[1,0]
	v_pk_mul_f32 v[118:119], v[118:119], v[156:157] op_sel_hi:[1,0]
	v_lshl_add_u64 v[158:159], v[158:159], 0, v[0:1]
	v_cvt_pk_bf16_f32 v124, v124, v125
	v_cvt_pk_bf16_f32 v125, v160, v161
	global_store_dwordx4 v[158:159], v[122:125], off offset:0 sc1
	s_nop 1
	v_pk_mul_f32 v[122:123], v[116:117], v[156:157] op_sel_hi:[1,0]
	v_pk_mul_f32 v[116:117], v[114:115], v[156:157] op_sel_hi:[1,0]
	v_mul_f32_e32 v114, v119, v119
	v_mul_f32_e32 v115, v121, v121
	v_fmac_f32_e32 v114, v118, v118
	v_fmac_f32_e32 v115, v120, v120
	v_add_f32_e32 v114, v114, v115
	v_mul_f32_e32 v115, v117, v117
	v_fmac_f32_e32 v115, v116, v116
	v_add_f32_e32 v114, v115, v114
	v_mul_f32_e32 v115, v123, v123
	v_fmac_f32_e32 v115, v122, v122
	v_add_f32_e32 v114, v115, v114
	v_cvt_pk_bf16_f32 v115, v120, v121
	v_add_f32_e32 v124, v155, v114
	v_cvt_pk_bf16_f32 v114, v118, v119
	v_cvt_pk_bf16_f32 v116, v116, v117
	v_cvt_pk_bf16_f32 v117, v122, v123
	global_store_dwordx4 v[158:159], v[114:117], off offset:0x100 sc1
	s_nop 1
	v_and_b32_e32 v115, 64, v238
	v_xor_b32_e32 v114, 16, v238
	v_add_u32_e32 v115, 64, v115
	v_cmp_lt_i32_e32 vcc, v114, v115
	v_xor_b32_e32 v117, 32, v238
	s_nop 0
	v_cndmask_b32_e32 v114, v238, v114, vcc
	v_lshlrev_b32_e32 v116, 2, v114
	ds_bpermute_b32 v114, v116, v124
	v_cmp_lt_i32_e32 vcc, v117, v115
	s_waitcnt lgkmcnt(0)
	v_add_f32_e32 v114, v124, v114
	v_cndmask_b32_e32 v115, v238, v117, vcc
	v_lshlrev_b32_e32 v117, 2, v115
	ds_bpermute_b32 v115, v117, v114
	s_and_saveexec_b64 s[36:37], s[8:9]
	s_cbranch_execz .LBB0_680
	v_lshlrev_b64 v[118:119], 6, v[144:145]
	v_lshl_add_u64 v[118:119], s[18:19], 0, v[118:119]
	v_lshl_add_u64 v[118:119], s[30:31], 2, v[118:119]
	s_lshl_b32 s76, s59, 2
	v_lshl_add_u64 v[118:119], v[118:119], 0, s[76:77]
	s_waitcnt lgkmcnt(0)
	v_add_f32_e32 v114, v114, v115
	global_store_dword v[118:119], v114, off

.LBB0_860:
	s_ashr_i32 s25, s24, 31
	s_lshl_b64 s[26:27], s[24:25], 19
	s_add_u32 s26, s42, s26
	s_addc_u32 s27, s43, s27
	s_and_b64 s[28:29], s[8:9], exec
	s_cselect_b32 s25, s27, s31
	s_cselect_b32 s73, s26, s30
	s_ashr_i32 s23, s22, 31
	s_lshl_b64 s[28:29], s[22:23], 19
	s_add_u32 s28, s44, s28
	s_addc_u32 s29, s45, s29
	s_and_b64 s[36:37], s[8:9], exec
	s_cselect_b32 s23, s29, s35
	s_cselect_b32 s74, s28, s34
	s_add_u32 s75, s73, 0x80
	s_addc_u32 s76, s25, 0
	s_add_u32 s36, s30, 0x40080
	s_addc_u32 s37, s31, 0
	s_add_u32 s78, s34, 0x100
	v_mov_b32_e32 v2, 0
	v_lshl_add_u64 v[142:143], s[36:37], 0, v[138:139]
	v_lshl_add_u64 v[144:145], s[36:37], 0, v[140:141]
	s_addc_u32 s85, s35, 0
	s_mov_b32 s86, -2
	s_mov_b64 s[34:35], 0
	v_mov_b32_e32 v3, v2
	v_mov_b32_e32 v4, v2
	v_mov_b32_e32 v5, v2
	v_mov_b32_e32 v6, v2
	v_mov_b32_e32 v7, v2
	v_mov_b32_e32 v8, v2
	v_mov_b32_e32 v9, v2
	v_mov_b32_e32 v18, v2
	v_mov_b32_e32 v19, v2
	v_mov_b32_e32 v20, v2
	v_mov_b32_e32 v21, v2
	v_mov_b32_e32 v22, v2
	v_mov_b32_e32 v23, v2
	v_mov_b32_e32 v24, v2
	v_mov_b32_e32 v25, v2
	v_mov_b32_e32 v34, v2
	v_mov_b32_e32 v35, v2
	v_mov_b32_e32 v36, v2
	v_mov_b32_e32 v37, v2
	v_mov_b32_e32 v38, v2
	v_mov_b32_e32 v39, v2
	v_mov_b32_e32 v40, v2
	v_mov_b32_e32 v41, v2
	v_mov_b32_e32 v50, v2
	v_mov_b32_e32 v51, v2
	v_mov_b32_e32 v52, v2
	v_mov_b32_e32 v53, v2
	v_mov_b32_e32 v54, v2
	v_mov_b32_e32 v55, v2
	v_mov_b32_e32 v56, v2
	v_mov_b32_e32 v57, v2
	v_mov_b32_e32 v10, v2
	v_mov_b32_e32 v11, v2
	v_mov_b32_e32 v12, v2
	v_mov_b32_e32 v13, v2
	v_mov_b32_e32 v14, v2
	v_mov_b32_e32 v15, v2
	v_mov_b32_e32 v16, v2
	v_mov_b32_e32 v17, v2
	v_mov_b32_e32 v26, v2
	v_mov_b32_e32 v27, v2
	v_mov_b32_e32 v28, v2
	v_mov_b32_e32 v29, v2
	v_mov_b32_e32 v30, v2
	v_mov_b32_e32 v31, v2
	v_mov_b32_e32 v32, v2
	v_mov_b32_e32 v33, v2
	v_mov_b32_e32 v42, v2
	v_mov_b32_e32 v43, v2
	v_mov_b32_e32 v44, v2
	v_mov_b32_e32 v45, v2
	v_mov_b32_e32 v46, v2
	v_mov_b32_e32 v47, v2
	v_mov_b32_e32 v48, v2
	v_mov_b32_e32 v49, v2
	v_mov_b32_e32 v58, v2
	v_mov_b32_e32 v59, v2
	v_mov_b32_e32 v60, v2
	v_mov_b32_e32 v61, v2
	v_mov_b32_e32 v62, v2
	v_mov_b32_e32 v63, v2
	v_mov_b32_e32 v64, v2
	v_mov_b32_e32 v65, v2
	v_mov_b32_e32 v66, v2
	v_mov_b32_e32 v67, v2
	v_mov_b32_e32 v68, v2
	v_mov_b32_e32 v69, v2
	v_mov_b32_e32 v70, v2
	v_mov_b32_e32 v71, v2
	v_mov_b32_e32 v72, v2
	v_mov_b32_e32 v73, v2
	v_mov_b32_e32 v82, v2
	v_mov_b32_e32 v83, v2
	v_mov_b32_e32 v84, v2
	v_mov_b32_e32 v85, v2
	v_mov_b32_e32 v86, v2
	v_mov_b32_e32 v87, v2
	v_mov_b32_e32 v88, v2
	v_mov_b32_e32 v89, v2
	v_mov_b32_e32 v98, v2
	v_mov_b32_e32 v99, v2
	v_mov_b32_e32 v100, v2
	v_mov_b32_e32 v101, v2
	v_mov_b32_e32 v102, v2
	v_mov_b32_e32 v103, v2
	v_mov_b32_e32 v104, v2
	v_mov_b32_e32 v105, v2
	v_mov_b32_e32 v114, v2
	v_mov_b32_e32 v115, v2
	v_mov_b32_e32 v116, v2
	v_mov_b32_e32 v117, v2
	v_mov_b32_e32 v118, v2
	v_mov_b32_e32 v119, v2
	v_mov_b32_e32 v120, v2
	v_mov_b32_e32 v121, v2
	v_mov_b32_e32 v74, v2
	v_mov_b32_e32 v75, v2
	v_mov_b32_e32 v76, v2
	v_mov_b32_e32 v77, v2
	v_mov_b32_e32 v78, v2
	v_mov_b32_e32 v79, v2
	v_mov_b32_e32 v80, v2
	v_mov_b32_e32 v81, v2
	v_mov_b32_e32 v90, v2
	v_mov_b32_e32 v91, v2
	v_mov_b32_e32 v92, v2
	v_mov_b32_e32 v93, v2
	v_mov_b32_e32 v94, v2
	v_mov_b32_e32 v95, v2
	v_mov_b32_e32 v96, v2
	v_mov_b32_e32 v97, v2
	v_mov_b32_e32 v106, v2
	v_mov_b32_e32 v107, v2
	v_mov_b32_e32 v108, v2
	v_mov_b32_e32 v109, v2
	v_mov_b32_e32 v110, v2
	v_mov_b32_e32 v111, v2
	v_mov_b32_e32 v112, v2
	v_mov_b32_e32 v113, v2
	v_mov_b32_e32 v122, v2
	v_mov_b32_e32 v123, v2
	v_mov_b32_e32 v124, v2
	v_mov_b32_e32 v125, v2
	v_mov_b32_e32 v126, v2
	v_mov_b32_e32 v127, v2
	v_mov_b32_e32 v128, v2
	v_mov_b32_e32 v129, v2
	v_lshl_add_u32 v252, s72, 8, v151
	v_ashrrev_i32_e32 v253, 31, v252
	v_lshl_add_u64 v[252:253], v[252:253], 2, s[10:11]
	global_load_dword v234, v[252:253], off
	global_load_dword v235, v[252:253], off offset:64
	global_load_dword v236, v[252:253], off offset:128
	global_load_dword v237, v[252:253], off offset:192
	global_load_dword v242, v[252:253], off offset:512
	global_load_dword v243, v[252:253], off offset:576
	global_load_dword v244, v[252:253], off offset:640
	global_load_dword v254, v[252:253], off offset:704
.LBB0_861:
	s_add_u32 s4, s30, s34
	s_addc_u32 s5, s31, s35
	s_add_u32 s40, s4, 0x100
	s_addc_u32 s41, s5, 0
	s_add_u32 s38, s78, s34
	s_addc_u32 s39, s85, s35
	s_add_u32 s4, s4, 0x180
	s_addc_u32 s5, s5, 0
	s_add_i32 s65, 0, 0x10000
	s_add_i32 s87, 0, 0x14000
	v_add_u32_e32 v162, s65, v152
	v_add_u32_e32 v178, s87, v152
	ds_read_b128 v[146:149], v162
	ds_read_b128 v[154:157], v162 offset:1024
	ds_read_b128 v[158:161], v162 offset:2048
	ds_read_b128 v[162:165], v162 offset:3072
	ds_read_b128 v[166:169], v178
	ds_read_b128 v[170:173], v178 offset:1024
	ds_read_b128 v[174:177], v178 offset:2048
	ds_read_b128 v[178:181], v178 offset:3072
	s_cmpk_eq_i32 s34, 0x700
	s_cselect_b32 s37, s76, s5
	s_cselect_b32 s36, s75, s4
	s_cselect_b32 s39, s23, s39
	s_cselect_b32 s38, s74, s38
	s_cselect_b32 s41, s25, s41
	s_cselect_b32 s40, s73, s40
	v_lshl_add_u64 v[194:195], v[142:143], 0, s[34:35]
	s_add_i32 m0, s56, 0xc000
	ds_read_b128 v[182:185], v153
	ds_read_b128 v[186:189], v153 offset:1024
	ds_read_b128 v[190:193], v153 offset:2048
	ds_read_b128 v[202:205], v153 offset:3072
	ds_read_b128 v[206:209], v153 offset:4096
	ds_read_b128 v[210:213], v153 offset:5120
	ds_read_b128 v[214:217], v153 offset:6144
	ds_read_b128 v[218:221], v153 offset:7168
	global_load_lds_dwordx4 v[194:195], off
	v_lshl_add_u64 v[194:195], v[144:145], 0, s[34:35]
	s_add_i32 m0, s56, 0xe000
	s_nop 0
	global_load_lds_dwordx4 v[194:195], off
	s_cmp_lg_u32 s86, -2
	s_cbranch_scc1 .Lg5wa_norm
	s_cmp_eq_u32 s70, 1
	s_cbranch_scc1 .Lg5wa_first
	s_waitcnt vmcnt(32)
	s_branch .Lg5wa_done

.Lg5wa_done:
	s_waitcnt lgkmcnt(0)
	s_barrier
	s_setprio 1
	s_waitcnt lgkmcnt(0)
	v_mfma_f32_16x16x32_bf16 v[126:129], v[146:149], v[182:185], v[126:129]
	v_mfma_f32_16x16x32_bf16 v[122:125], v[158:161], v[182:185], v[122:125]
	v_mfma_f32_16x16x32_bf16 v[110:113], v[146:149], v[190:193], v[110:113]
	v_mfma_f32_16x16x32_bf16 v[106:109], v[158:161], v[190:193], v[106:109]
	v_mfma_f32_16x16x32_bf16 v[94:97], v[146:149], v[206:209], v[94:97]
	v_mfma_f32_16x16x32_bf16 v[90:93], v[158:161], v[206:209], v[90:93]
	v_mfma_f32_16x16x32_bf16 v[78:81], v[146:149], v[214:217], v[78:81]
	v_mfma_f32_16x16x32_bf16 v[74:77], v[158:161], v[214:217], v[74:77]
	v_mfma_f32_16x16x32_bf16 v[126:129], v[154:157], v[186:189], v[126:129]
	v_mfma_f32_16x16x32_bf16 v[122:125], v[162:165], v[186:189], v[122:125]
	v_mfma_f32_16x16x32_bf16 v[110:113], v[154:157], v[202:205], v[110:113]
	v_mfma_f32_16x16x32_bf16 v[106:109], v[162:165], v[202:205], v[106:109]
	v_mfma_f32_16x16x32_bf16 v[94:97], v[154:157], v[210:213], v[94:97]
	v_mfma_f32_16x16x32_bf16 v[90:93], v[162:165], v[210:213], v[90:93]
	v_mfma_f32_16x16x32_bf16 v[78:81], v[154:157], v[218:221], v[78:81]
	v_mfma_f32_16x16x32_bf16 v[74:77], v[162:165], v[218:221], v[74:77]
	s_setprio 0
	s_setprio 1
	v_mfma_f32_16x16x32_bf16 v[118:121], v[166:169], v[182:185], v[118:121]
	v_mfma_f32_16x16x32_bf16 v[114:117], v[174:177], v[182:185], v[114:117]
	v_mfma_f32_16x16x32_bf16 v[102:105], v[166:169], v[190:193], v[102:105]
	v_mfma_f32_16x16x32_bf16 v[98:101], v[174:177], v[190:193], v[98:101]
	v_mfma_f32_16x16x32_bf16 v[86:89], v[166:169], v[206:209], v[86:89]
	v_mfma_f32_16x16x32_bf16 v[82:85], v[174:177], v[206:209], v[82:85]
	v_mfma_f32_16x16x32_bf16 v[70:73], v[166:169], v[214:217], v[70:73]
	v_mfma_f32_16x16x32_bf16 v[66:69], v[174:177], v[214:217], v[66:69]
	v_mfma_f32_16x16x32_bf16 v[118:121], v[170:173], v[186:189], v[118:121]
	v_mfma_f32_16x16x32_bf16 v[114:117], v[178:181], v[186:189], v[114:117]
	v_mfma_f32_16x16x32_bf16 v[102:105], v[170:173], v[202:205], v[102:105]
	v_mfma_f32_16x16x32_bf16 v[98:101], v[178:181], v[202:205], v[98:101]
	v_mfma_f32_16x16x32_bf16 v[86:89], v[170:173], v[210:213], v[86:89]
	v_mfma_f32_16x16x32_bf16 v[82:85], v[178:181], v[210:213], v[82:85]
	v_mfma_f32_16x16x32_bf16 v[70:73], v[170:173], v[218:221], v[70:73]
	v_mfma_f32_16x16x32_bf16 v[66:69], v[178:181], v[218:221], v[66:69]
	s_setprio 0
	s_barrier
	s_add_i32 s4, s65, s51
	v_lshl_add_u64 v[194:195], s[38:39], 0, v[134:135]
	s_mov_b32 m0, s4
	ds_read_b128 v[182:185], v153 offset:16384
	ds_read_b128 v[186:189], v153 offset:17408
	ds_read_b128 v[190:193], v153 offset:18432
	ds_read_b128 v[202:205], v153 offset:19456
	ds_read_b128 v[206:209], v153 offset:20480
	ds_read_b128 v[210:213], v153 offset:21504
	ds_read_b128 v[214:217], v153 offset:22528
	ds_read_b128 v[218:221], v153 offset:23552
	global_load_lds_dwordx4 v[194:195], off
	s_add_i32 m0, s4, 0x2000
	s_add_u32 vcc_lo, s38, 0x40000
	v_lshl_add_u64 v[198:199], s[38:39], 0, v[130:131]
	s_addc_u32 vcc_hi, s39, 0
	s_add_i32 s4, s87, s51
	global_load_lds_dwordx4 v[198:199], off
	v_lshl_add_u64 v[222:223], vcc, 0, v[134:135]
	s_mov_b32 m0, s4
	s_nop 0
	global_load_lds_dwordx4 v[222:223], off
	v_lshl_add_u64 v[222:223], vcc, 0, v[130:131]
	s_add_i32 m0, s4, 0x2000
	s_nop 0
	global_load_lds_dwordx4 v[222:223], off
	v_lshl_add_u64 v[222:223], s[40:41], 0, v[136:137]
	s_mov_b32 m0, s56
	s_nop 0
	global_load_lds_dwordx4 v[222:223], off
	v_lshl_add_u64 v[222:223], s[40:41], 0, v[132:133]
	s_mov_b32 m0, s57
	s_nop 0
	global_load_lds_dwordx4 v[222:223], off
	s_cmp_lg_u32 s86, -2
	s_cbranch_scc1 .Lg5wb_norm
	s_cmp_eq_u32 s70, 1
	s_cbranch_scc1 .Lg5wb_first
	s_waitcnt vmcnt(32)
	s_branch .Lg5wb_done

.Lg5wb_done:
	s_waitcnt lgkmcnt(0)
	s_barrier
	s_setprio 1
	s_waitcnt lgkmcnt(0)
	v_mfma_f32_16x16x32_bf16 v[62:65], v[146:149], v[182:185], v[62:65]
	v_mfma_f32_16x16x32_bf16 v[58:61], v[158:161], v[182:185], v[58:61]
	v_mfma_f32_16x16x32_bf16 v[46:49], v[146:149], v[190:193], v[46:49]
	v_mfma_f32_16x16x32_bf16 v[42:45], v[158:161], v[190:193], v[42:45]
	v_mfma_f32_16x16x32_bf16 v[30:33], v[146:149], v[206:209], v[30:33]
	v_mfma_f32_16x16x32_bf16 v[26:29], v[158:161], v[206:209], v[26:29]
	v_mfma_f32_16x16x32_bf16 v[14:17], v[146:149], v[214:217], v[14:17]
	v_mfma_f32_16x16x32_bf16 v[10:13], v[158:161], v[214:217], v[10:13]
	v_mfma_f32_16x16x32_bf16 v[62:65], v[154:157], v[186:189], v[62:65]
	v_mfma_f32_16x16x32_bf16 v[58:61], v[162:165], v[186:189], v[58:61]
	v_mfma_f32_16x16x32_bf16 v[46:49], v[154:157], v[202:205], v[46:49]
	v_mfma_f32_16x16x32_bf16 v[42:45], v[162:165], v[202:205], v[42:45]
	v_mfma_f32_16x16x32_bf16 v[30:33], v[154:157], v[210:213], v[30:33]
	v_mfma_f32_16x16x32_bf16 v[26:29], v[162:165], v[210:213], v[26:29]
	v_mfma_f32_16x16x32_bf16 v[14:17], v[154:157], v[218:221], v[14:17]
	v_mfma_f32_16x16x32_bf16 v[10:13], v[162:165], v[218:221], v[10:13]
	s_setprio 0
	s_setprio 1
	v_mfma_f32_16x16x32_bf16 v[54:57], v[166:169], v[182:185], v[54:57]
	v_mfma_f32_16x16x32_bf16 v[50:53], v[174:177], v[182:185], v[50:53]
	v_mfma_f32_16x16x32_bf16 v[38:41], v[166:169], v[190:193], v[38:41]
	v_mfma_f32_16x16x32_bf16 v[34:37], v[174:177], v[190:193], v[34:37]
	v_mfma_f32_16x16x32_bf16 v[22:25], v[166:169], v[206:209], v[22:25]
	v_mfma_f32_16x16x32_bf16 v[18:21], v[174:177], v[206:209], v[18:21]
	v_mfma_f32_16x16x32_bf16 v[6:9], v[166:169], v[214:217], v[6:9]
	v_mfma_f32_16x16x32_bf16 v[2:5], v[174:177], v[214:217], v[2:5]
	v_mfma_f32_16x16x32_bf16 v[54:57], v[170:173], v[186:189], v[54:57]
	v_mfma_f32_16x16x32_bf16 v[50:53], v[178:181], v[186:189], v[50:53]
	v_mfma_f32_16x16x32_bf16 v[38:41], v[170:173], v[202:205], v[38:41]
	v_mfma_f32_16x16x32_bf16 v[34:37], v[178:181], v[202:205], v[34:37]
	v_mfma_f32_16x16x32_bf16 v[22:25], v[170:173], v[210:213], v[22:25]
	v_mfma_f32_16x16x32_bf16 v[18:21], v[178:181], v[210:213], v[18:21]
	v_mfma_f32_16x16x32_bf16 v[6:9], v[170:173], v[218:221], v[6:9]
	v_mfma_f32_16x16x32_bf16 v[2:5], v[178:181], v[218:221], v[2:5]
	s_setprio 0
	s_barrier
	s_add_i32 s4, 0, 0x18000
	s_add_i32 s5, 0, 0x1c000
	v_add_u32_e32 v162, s4, v152
	v_add_u32_e32 v178, s5, v152
	ds_read_b128 v[146:149], v162
	ds_read_b128 v[154:157], v162 offset:1024
	ds_read_b128 v[158:161], v162 offset:2048
	ds_read_b128 v[162:165], v162 offset:3072
	ds_read_b128 v[166:169], v178
	ds_read_b128 v[170:173], v178 offset:1024
	ds_read_b128 v[174:177], v178 offset:2048
	ds_read_b128 v[178:181], v178 offset:3072
	s_add_u32 s40, s40, 0x40000
	s_addc_u32 s41, s41, 0
	s_mov_b32 m0, s58
	v_lshl_add_u64 v[222:223], s[40:41], 0, v[136:137]
	ds_read_b128 v[182:185], v153 offset:32768
	ds_read_b128 v[186:189], v153 offset:33792
	ds_read_b128 v[190:193], v153 offset:34816
	ds_read_b128 v[202:205], v153 offset:35840
	ds_read_b128 v[206:209], v153 offset:36864
	ds_read_b128 v[210:213], v153 offset:37888
	ds_read_b128 v[214:217], v153 offset:38912
	ds_read_b128 v[218:221], v153 offset:39936
	global_load_lds_dwordx4 v[222:223], off
	v_lshl_add_u64 v[222:223], s[40:41], 0, v[132:133]
	s_mov_b32 m0, s59
	s_nop 0
	global_load_lds_dwordx4 v[222:223], off
	s_waitcnt vmcnt(8)
	s_waitcnt lgkmcnt(0)
	s_barrier
	s_setprio 1
	s_waitcnt lgkmcnt(0)
	v_mfma_f32_16x16x32_bf16 v[126:129], v[146:149], v[182:185], v[126:129]
	v_mfma_f32_16x16x32_bf16 v[122:125], v[158:161], v[182:185], v[122:125]
	v_mfma_f32_16x16x32_bf16 v[110:113], v[146:149], v[190:193], v[110:113]
	v_mfma_f32_16x16x32_bf16 v[106:109], v[158:161], v[190:193], v[106:109]
	v_mfma_f32_16x16x32_bf16 v[94:97], v[146:149], v[206:209], v[94:97]
	v_mfma_f32_16x16x32_bf16 v[90:93], v[158:161], v[206:209], v[90:93]
	v_mfma_f32_16x16x32_bf16 v[78:81], v[146:149], v[214:217], v[78:81]
	v_mfma_f32_16x16x32_bf16 v[74:77], v[158:161], v[214:217], v[74:77]
	v_mfma_f32_16x16x32_bf16 v[126:129], v[154:157], v[186:189], v[126:129]
	v_mfma_f32_16x16x32_bf16 v[122:125], v[162:165], v[186:189], v[122:125]
	v_mfma_f32_16x16x32_bf16 v[110:113], v[154:157], v[202:205], v[110:113]
	v_mfma_f32_16x16x32_bf16 v[106:109], v[162:165], v[202:205], v[106:109]
	v_mfma_f32_16x16x32_bf16 v[94:97], v[154:157], v[210:213], v[94:97]
	v_mfma_f32_16x16x32_bf16 v[90:93], v[162:165], v[210:213], v[90:93]
	v_mfma_f32_16x16x32_bf16 v[78:81], v[154:157], v[218:221], v[78:81]
	v_mfma_f32_16x16x32_bf16 v[74:77], v[162:165], v[218:221], v[74:77]
	s_setprio 0
	s_setprio 1
	v_mfma_f32_16x16x32_bf16 v[118:121], v[166:169], v[182:185], v[118:121]
	v_mfma_f32_16x16x32_bf16 v[114:117], v[174:177], v[182:185], v[114:117]
	v_mfma_f32_16x16x32_bf16 v[102:105], v[166:169], v[190:193], v[102:105]
	v_mfma_f32_16x16x32_bf16 v[98:101], v[174:177], v[190:193], v[98:101]
	v_mfma_f32_16x16x32_bf16 v[86:89], v[166:169], v[206:209], v[86:89]
	v_mfma_f32_16x16x32_bf16 v[82:85], v[174:177], v[206:209], v[82:85]
	v_mfma_f32_16x16x32_bf16 v[70:73], v[166:169], v[214:217], v[70:73]
	v_mfma_f32_16x16x32_bf16 v[66:69], v[174:177], v[214:217], v[66:69]
	v_mfma_f32_16x16x32_bf16 v[118:121], v[170:173], v[186:189], v[118:121]
	v_mfma_f32_16x16x32_bf16 v[114:117], v[178:181], v[186:189], v[114:117]
	v_mfma_f32_16x16x32_bf16 v[102:105], v[170:173], v[202:205], v[102:105]
	v_mfma_f32_16x16x32_bf16 v[98:101], v[178:181], v[202:205], v[98:101]
	v_mfma_f32_16x16x32_bf16 v[86:89], v[170:173], v[210:213], v[86:89]
	v_mfma_f32_16x16x32_bf16 v[82:85], v[178:181], v[210:213], v[82:85]
	v_mfma_f32_16x16x32_bf16 v[70:73], v[170:173], v[218:221], v[70:73]
	v_mfma_f32_16x16x32_bf16 v[66:69], v[178:181], v[218:221], v[66:69]
	s_setprio 0
	s_barrier
	s_add_i32 s4, s4, s51
	v_lshl_add_u64 v[194:195], v[194:195], 0, s[90:91]
	s_mov_b32 m0, s4
	ds_read_b128 v[182:185], v153 offset:49152
	ds_read_b128 v[186:189], v153 offset:50176
	ds_read_b128 v[190:193], v153 offset:51200
	ds_read_b128 v[202:205], v153 offset:52224
	ds_read_b128 v[206:209], v153 offset:53248
	ds_read_b128 v[210:213], v153 offset:54272
	ds_read_b128 v[214:217], v153 offset:55296
	ds_read_b128 v[218:221], v153 offset:56320
	global_load_lds_dwordx4 v[194:195], off
	s_add_i32 m0, s4, 0x2000
	s_add_u32 s38, s38, 0x40080
	v_lshl_add_u64 v[194:195], v[198:199], 0, s[90:91]
	s_addc_u32 s39, s39, 0
	s_add_i32 s4, s5, s51
	global_load_lds_dwordx4 v[194:195], off
	v_lshl_add_u64 v[194:195], s[38:39], 0, v[134:135]
	s_mov_b32 m0, s4
	s_nop 0
	global_load_lds_dwordx4 v[194:195], off
	v_lshl_add_u64 v[194:195], s[38:39], 0, v[130:131]
	s_add_i32 m0, s4, 0x2000
	s_nop 0
	global_load_lds_dwordx4 v[194:195], off
	v_lshl_add_u64 v[194:195], s[36:37], 0, v[136:137]
	s_mov_b32 m0, s68
	s_nop 0
	global_load_lds_dwordx4 v[194:195], off
	v_lshl_add_u64 v[194:195], s[36:37], 0, v[132:133]
	s_mov_b32 m0, s69
	s_nop 0
	global_load_lds_dwordx4 v[194:195], off
	s_waitcnt vmcnt(8)
	s_waitcnt lgkmcnt(0)
	s_barrier
	s_setprio 1
	s_waitcnt lgkmcnt(0)
	v_mfma_f32_16x16x32_bf16 v[62:65], v[146:149], v[182:185], v[62:65]
	v_mfma_f32_16x16x32_bf16 v[58:61], v[158:161], v[182:185], v[58:61]
	v_mfma_f32_16x16x32_bf16 v[46:49], v[146:149], v[190:193], v[46:49]
	v_mfma_f32_16x16x32_bf16 v[42:45], v[158:161], v[190:193], v[42:45]
	v_mfma_f32_16x16x32_bf16 v[30:33], v[146:149], v[206:209], v[30:33]
	v_mfma_f32_16x16x32_bf16 v[26:29], v[158:161], v[206:209], v[26:29]
	v_mfma_f32_16x16x32_bf16 v[14:17], v[146:149], v[214:217], v[14:17]
	v_mfma_f32_16x16x32_bf16 v[10:13], v[158:161], v[214:217], v[10:13]
	v_mfma_f32_16x16x32_bf16 v[62:65], v[154:157], v[186:189], v[62:65]
	v_mfma_f32_16x16x32_bf16 v[58:61], v[162:165], v[186:189], v[58:61]
	v_mfma_f32_16x16x32_bf16 v[46:49], v[154:157], v[202:205], v[46:49]
	v_mfma_f32_16x16x32_bf16 v[42:45], v[162:165], v[202:205], v[42:45]
	v_mfma_f32_16x16x32_bf16 v[30:33], v[154:157], v[210:213], v[30:33]
	v_mfma_f32_16x16x32_bf16 v[26:29], v[162:165], v[210:213], v[26:29]
	v_mfma_f32_16x16x32_bf16 v[14:17], v[154:157], v[218:221], v[14:17]
	v_mfma_f32_16x16x32_bf16 v[10:13], v[162:165], v[218:221], v[10:13]
	s_setprio 0
	s_setprio 1
	v_mfma_f32_16x16x32_bf16 v[54:57], v[166:169], v[182:185], v[54:57]
	v_mfma_f32_16x16x32_bf16 v[50:53], v[174:177], v[182:185], v[50:53]
	v_mfma_f32_16x16x32_bf16 v[38:41], v[166:169], v[190:193], v[38:41]
	v_mfma_f32_16x16x32_bf16 v[34:37], v[174:177], v[190:193], v[34:37]
	v_mfma_f32_16x16x32_bf16 v[22:25], v[166:169], v[206:209], v[22:25]
	v_mfma_f32_16x16x32_bf16 v[18:21], v[174:177], v[206:209], v[18:21]
	v_mfma_f32_16x16x32_bf16 v[6:9], v[166:169], v[214:217], v[6:9]
	v_mfma_f32_16x16x32_bf16 v[2:5], v[174:177], v[214:217], v[2:5]
	v_mfma_f32_16x16x32_bf16 v[54:57], v[170:173], v[186:189], v[54:57]
	v_mfma_f32_16x16x32_bf16 v[50:53], v[178:181], v[186:189], v[50:53]
	v_mfma_f32_16x16x32_bf16 v[38:41], v[170:173], v[202:205], v[38:41]
	v_mfma_f32_16x16x32_bf16 v[34:37], v[178:181], v[202:205], v[34:37]
	v_mfma_f32_16x16x32_bf16 v[22:25], v[170:173], v[210:213], v[22:25]
	v_mfma_f32_16x16x32_bf16 v[18:21], v[178:181], v[210:213], v[18:21]
	v_mfma_f32_16x16x32_bf16 v[6:9], v[170:173], v[218:221], v[6:9]
	v_mfma_f32_16x16x32_bf16 v[2:5], v[178:181], v[218:221], v[2:5]
	s_setprio 0
	s_barrier
	s_add_i32 s86, s86, 2
	s_add_u32 s34, s34, 0x100
	s_addc_u32 s35, s35, 0
	s_cmp_gt_u32 s86, 13
	s_cbranch_scc0 .LBB0_861
	s_and_b64 vcc, exec, s[20:21]
	s_cbranch_vccz .LBB0_864
	s_barrier
.LBB0_864:
	v_lshl_add_u32 v142, s72, 8, v151
	v_ashrrev_i32_e32 v143, 31, v142
	v_mov_b32_e32 v162, v234
	v_mov_b32_e32 v163, v235
	v_mov_b32_e32 v159, v236
	v_mov_b32_e32 v158, v237
	v_mov_b32_e32 v157, v242
	v_mov_b32_e32 v156, v243
	v_mov_b32_e32 v155, v244
	v_mov_b32_e32 v154, v254
	s_lshl_b32 s30, s71, 8
	v_or_b32_e32 v148, 16, v142
	v_or_b32_e32 v146, 32, v142
	v_or_b32_e32 v144, 48, v142
	s_ashr_i32 s31, s30, 31
	v_lshlrev_b64 v[142:143], 13, v[142:143]
	v_ashrrev_i32_e32 v149, 31, v148
	v_lshl_add_u64 v[142:143], s[18:19], 0, v[142:143]
	s_lshl_b64 s[30:31], s[30:31], 1
	v_lshl_add_u64 v[142:143], v[142:143], 0, s[30:31]
	v_ashrrev_i32_e32 v147, 31, v146
	v_lshl_add_u64 v[142:143], v[142:143], 0, v[0:1]
	v_ashrrev_i32_e32 v145, 31, v144
	v_fmamk_f32 v160, v162, 0x3a800000, v233
	v_cmp_gt_f32_e32 vcc, s82, v160
	v_mul_f32_e32 v161, 0x4b800000, v160
	s_nop 0
	v_cndmask_b32_e32 v160, v160, v161, vcc
	v_rsq_f32_e32 v160, v160
	s_nop 0
	v_mul_f32_e32 v161, 0x45800000, v160
	v_cndmask_b32_e32 v160, v160, v161, vcc
	v_pk_mul_f32 v[120:121], v[120:121], v[160:161] op_sel_hi:[1,0]
	v_pk_mul_f32 v[118:119], v[118:119], v[160:161] op_sel_hi:[1,0]
	v_pk_mul_f32 v[114:115], v[114:115], v[160:161] op_sel_hi:[1,0]
	v_max_f32_e32 v118, 0, v118
	v_max_f32_e32 v119, 0, v119
	v_max_f32_e32 v120, 0, v120
	v_max_f32_e32 v121, 0, v121
	v_max_f32_e32 v114, 0, v114
	v_max_f32_e32 v115, 0, v115
	v_pk_mul_f32 v[118:119], v[118:119], v[118:119]
	v_pk_mul_f32 v[120:121], v[120:121], v[120:121]
	v_pk_mul_f32 v[116:117], v[116:117], v[160:161] op_sel_hi:[1,0]
	v_pk_mul_f32 v[114:115], v[114:115], v[114:115]
	v_cvt_pk_bf16_f32 v118, v118, v119
	v_cvt_pk_bf16_f32 v119, v120, v121
	v_cvt_pk_bf16_f32 v120, v114, v115
	v_max_f32_e32 v114, 0, v116
	v_max_f32_e32 v115, 0, v117
	v_pk_mul_f32 v[114:115], v[114:115], v[114:115]
	v_pk_mul_f32 v[128:129], v[128:129], v[160:161] op_sel_hi:[1,0]
	v_cvt_pk_bf16_f32 v121, v114, v115
	v_fmamk_f32 v114, v163, 0x3a800000, v233
	v_cmp_gt_f32_e32 vcc, s82, v114
	v_mul_f32_e32 v115, 0x4b800000, v114
	v_pk_mul_f32 v[126:127], v[126:127], v[160:161] op_sel_hi:[1,0]
	v_cndmask_b32_e32 v114, v114, v115, vcc
	v_rsq_f32_e32 v114, v114
	v_pk_mul_f32 v[122:123], v[122:123], v[160:161] op_sel_hi:[1,0]
	v_max_f32_e32 v126, 0, v126
	v_max_f32_e32 v127, 0, v127
	v_mul_f32_e32 v115, 0x45800000, v114
	v_cndmask_b32_e32 v114, v114, v115, vcc
	v_pk_mul_f32 v[104:105], v[104:105], v[114:115] op_sel_hi:[1,0]
	v_pk_mul_f32 v[102:103], v[102:103], v[114:115] op_sel_hi:[1,0]
	v_pk_mul_f32 v[98:99], v[98:99], v[114:115] op_sel_hi:[1,0]
	v_max_f32_e32 v102, 0, v102
	v_max_f32_e32 v103, 0, v103
	v_max_f32_e32 v104, 0, v104
	v_max_f32_e32 v105, 0, v105
	v_max_f32_e32 v98, 0, v98
	v_max_f32_e32 v99, 0, v99
	v_pk_mul_f32 v[102:103], v[102:103], v[102:103]
	v_pk_mul_f32 v[104:105], v[104:105], v[104:105]
	v_pk_mul_f32 v[100:101], v[100:101], v[114:115] op_sel_hi:[1,0]
	v_pk_mul_f32 v[98:99], v[98:99], v[98:99]
	v_cvt_pk_bf16_f32 v102, v102, v103
	v_cvt_pk_bf16_f32 v103, v104, v105
	v_cvt_pk_bf16_f32 v104, v98, v99
	v_max_f32_e32 v98, 0, v100
	v_max_f32_e32 v99, 0, v101
	v_pk_mul_f32 v[98:99], v[98:99], v[98:99]
	v_max_f32_e32 v128, 0, v128
	v_cvt_pk_bf16_f32 v105, v98, v99
	v_fmamk_f32 v98, v159, 0x3a800000, v233
	v_cmp_gt_f32_e32 vcc, s82, v98
	v_mul_f32_e32 v99, 0x4b800000, v98
	v_max_f32_e32 v129, 0, v129
	v_cndmask_b32_e32 v98, v98, v99, vcc
	v_rsq_f32_e32 v98, v98
	v_max_f32_e32 v122, 0, v122
	v_max_f32_e32 v123, 0, v123
	v_pk_mul_f32 v[126:127], v[126:127], v[126:127]
	v_mul_f32_e32 v99, 0x45800000, v98
	v_cndmask_b32_e32 v98, v98, v99, vcc
	v_pk_mul_f32 v[88:89], v[88:89], v[98:99] op_sel_hi:[1,0]
	v_pk_mul_f32 v[86:87], v[86:87], v[98:99] op_sel_hi:[1,0]
	v_pk_mul_f32 v[82:83], v[82:83], v[98:99] op_sel_hi:[1,0]
	v_max_f32_e32 v86, 0, v86
	v_max_f32_e32 v87, 0, v87
	v_max_f32_e32 v88, 0, v88
	v_max_f32_e32 v89, 0, v89
	v_max_f32_e32 v82, 0, v82
	v_max_f32_e32 v83, 0, v83
	v_pk_mul_f32 v[86:87], v[86:87], v[86:87]
	v_pk_mul_f32 v[88:89], v[88:89], v[88:89]
	v_pk_mul_f32 v[84:85], v[84:85], v[98:99] op_sel_hi:[1,0]
	v_pk_mul_f32 v[82:83], v[82:83], v[82:83]
	v_cvt_pk_bf16_f32 v86, v86, v87
	v_cvt_pk_bf16_f32 v87, v88, v89
	v_cvt_pk_bf16_f32 v88, v82, v83
	v_max_f32_e32 v82, 0, v84
	v_max_f32_e32 v83, 0, v85
	v_pk_mul_f32 v[82:83], v[82:83], v[82:83]
	v_pk_mul_f32 v[128:129], v[128:129], v[128:129]
	v_cvt_pk_bf16_f32 v89, v82, v83
	v_fmamk_f32 v82, v158, 0x3a800000, v233
	v_cmp_gt_f32_e32 vcc, s82, v82
	v_mul_f32_e32 v83, 0x4b800000, v82
	v_pk_mul_f32 v[124:125], v[124:125], v[160:161] op_sel_hi:[1,0]
	v_cndmask_b32_e32 v82, v82, v83, vcc
	v_rsq_f32_e32 v82, v82
	v_pk_mul_f32 v[122:123], v[122:123], v[122:123]
	v_pk_mul_f32 v[112:113], v[112:113], v[114:115] op_sel_hi:[1,0]
	v_pk_mul_f32 v[110:111], v[110:111], v[114:115] op_sel_hi:[1,0]
	v_mul_f32_e32 v83, 0x45800000, v82
	v_cndmask_b32_e32 v82, v82, v83, vcc
	v_pk_mul_f32 v[72:73], v[72:73], v[82:83] op_sel_hi:[1,0]
	v_pk_mul_f32 v[70:71], v[70:71], v[82:83] op_sel_hi:[1,0]
	v_pk_mul_f32 v[66:67], v[66:67], v[82:83] op_sel_hi:[1,0]
	v_max_f32_e32 v70, 0, v70
	v_max_f32_e32 v71, 0, v71
	v_max_f32_e32 v72, 0, v72
	v_max_f32_e32 v73, 0, v73
	v_max_f32_e32 v66, 0, v66
	v_max_f32_e32 v67, 0, v67
	v_pk_mul_f32 v[70:71], v[70:71], v[70:71]
	v_pk_mul_f32 v[72:73], v[72:73], v[72:73]
	v_pk_mul_f32 v[68:69], v[68:69], v[82:83] op_sel_hi:[1,0]
	v_pk_mul_f32 v[66:67], v[66:67], v[66:67]
	v_cvt_pk_bf16_f32 v70, v70, v71
	v_cvt_pk_bf16_f32 v71, v72, v73
	v_cvt_pk_bf16_f32 v72, v66, v67
	v_max_f32_e32 v66, 0, v68
	v_max_f32_e32 v67, 0, v69
	v_pk_mul_f32 v[66:67], v[66:67], v[66:67]
	v_pk_mul_f32 v[106:107], v[106:107], v[114:115] op_sel_hi:[1,0]
	v_cvt_pk_bf16_f32 v73, v66, v67
	v_fmamk_f32 v66, v157, 0x3a800000, v233
	v_cmp_gt_f32_e32 vcc, s82, v66
	v_mul_f32_e32 v67, 0x4b800000, v66
	v_cvt_pk_bf16_f32 v126, v126, v127
	v_cndmask_b32_e32 v66, v66, v67, vcc
	v_rsq_f32_e32 v66, v66
	v_cvt_pk_bf16_f32 v127, v128, v129
	v_cvt_pk_bf16_f32 v128, v122, v123
	v_max_f32_e32 v122, 0, v124
	v_mul_f32_e32 v67, 0x45800000, v66
	v_cndmask_b32_e32 v66, v66, v67, vcc
	v_pk_mul_f32 v[56:57], v[56:57], v[66:67] op_sel_hi:[1,0]
	v_pk_mul_f32 v[54:55], v[54:55], v[66:67] op_sel_hi:[1,0]
	v_pk_mul_f32 v[50:51], v[50:51], v[66:67] op_sel_hi:[1,0]
	v_max_f32_e32 v54, 0, v54
	v_max_f32_e32 v55, 0, v55
	v_max_f32_e32 v56, 0, v56
	v_max_f32_e32 v57, 0, v57
	v_max_f32_e32 v50, 0, v50
	v_max_f32_e32 v51, 0, v51
	v_pk_mul_f32 v[54:55], v[54:55], v[54:55]
	v_pk_mul_f32 v[56:57], v[56:57], v[56:57]
	v_pk_mul_f32 v[52:53], v[52:53], v[66:67] op_sel_hi:[1,0]
	v_pk_mul_f32 v[50:51], v[50:51], v[50:51]
	v_cvt_pk_bf16_f32 v54, v54, v55
	v_cvt_pk_bf16_f32 v55, v56, v57
	v_cvt_pk_bf16_f32 v56, v50, v51
	v_max_f32_e32 v50, 0, v52
	v_max_f32_e32 v51, 0, v53
	v_pk_mul_f32 v[50:51], v[50:51], v[50:51]
	v_max_f32_e32 v123, 0, v125
	v_cvt_pk_bf16_f32 v57, v50, v51
	v_fmamk_f32 v50, v156, 0x3a800000, v233
	v_cmp_gt_f32_e32 vcc, s82, v50
	v_mul_f32_e32 v51, 0x4b800000, v50
	v_max_f32_e32 v110, 0, v110
	v_cndmask_b32_e32 v50, v50, v51, vcc
	v_rsq_f32_e32 v50, v50
	v_max_f32_e32 v111, 0, v111
	v_max_f32_e32 v112, 0, v112
	v_max_f32_e32 v113, 0, v113
	v_mul_f32_e32 v51, 0x45800000, v50
	v_cndmask_b32_e32 v50, v50, v51, vcc
	v_pk_mul_f32 v[40:41], v[40:41], v[50:51] op_sel_hi:[1,0]
	v_pk_mul_f32 v[38:39], v[38:39], v[50:51] op_sel_hi:[1,0]
	v_pk_mul_f32 v[34:35], v[34:35], v[50:51] op_sel_hi:[1,0]
	v_max_f32_e32 v38, 0, v38
	v_max_f32_e32 v39, 0, v39
	v_max_f32_e32 v40, 0, v40
	v_max_f32_e32 v41, 0, v41
	v_max_f32_e32 v34, 0, v34
	v_max_f32_e32 v35, 0, v35
	v_pk_mul_f32 v[38:39], v[38:39], v[38:39]
	v_pk_mul_f32 v[40:41], v[40:41], v[40:41]
	v_pk_mul_f32 v[36:37], v[36:37], v[50:51] op_sel_hi:[1,0]
	v_pk_mul_f32 v[34:35], v[34:35], v[34:35]
	v_cvt_pk_bf16_f32 v38, v38, v39
	v_cvt_pk_bf16_f32 v39, v40, v41
	v_cvt_pk_bf16_f32 v40, v34, v35
	v_max_f32_e32 v34, 0, v36
	v_max_f32_e32 v35, 0, v37
	v_pk_mul_f32 v[34:35], v[34:35], v[34:35]
	v_max_f32_e32 v106, 0, v106
	v_cvt_pk_bf16_f32 v41, v34, v35
	v_fmamk_f32 v34, v155, 0x3a800000, v233
	v_cmp_gt_f32_e32 vcc, s82, v34
	v_mul_f32_e32 v35, 0x4b800000, v34
	v_max_f32_e32 v107, 0, v107
	v_cndmask_b32_e32 v34, v34, v35, vcc
	v_rsq_f32_e32 v34, v34
	v_pk_mul_f32 v[122:123], v[122:123], v[122:123]
	v_lshlrev_b64 v[116:117], 13, v[148:149]
	v_pk_mul_f32 v[110:111], v[110:111], v[110:111]
	v_mul_f32_e32 v35, 0x45800000, v34
	v_cndmask_b32_e32 v34, v34, v35, vcc
	v_pk_mul_f32 v[24:25], v[24:25], v[34:35] op_sel_hi:[1,0]
	v_pk_mul_f32 v[22:23], v[22:23], v[34:35] op_sel_hi:[1,0]
	v_pk_mul_f32 v[18:19], v[18:19], v[34:35] op_sel_hi:[1,0]
	v_max_f32_e32 v22, 0, v22
	v_max_f32_e32 v23, 0, v23
	v_max_f32_e32 v24, 0, v24
	v_max_f32_e32 v25, 0, v25
	v_max_f32_e32 v18, 0, v18
	v_max_f32_e32 v19, 0, v19
	v_pk_mul_f32 v[22:23], v[22:23], v[22:23]
	v_pk_mul_f32 v[24:25], v[24:25], v[24:25]
	v_pk_mul_f32 v[20:21], v[20:21], v[34:35] op_sel_hi:[1,0]
	v_pk_mul_f32 v[18:19], v[18:19], v[18:19]
	v_cvt_pk_bf16_f32 v22, v22, v23
	v_cvt_pk_bf16_f32 v23, v24, v25
	v_cvt_pk_bf16_f32 v24, v18, v19
	v_max_f32_e32 v18, 0, v20
	v_max_f32_e32 v19, 0, v21
	v_pk_mul_f32 v[112:113], v[112:113], v[112:113]
	v_pk_mul_f32 v[108:109], v[108:109], v[114:115] op_sel_hi:[1,0]
	v_pk_mul_f32 v[106:107], v[106:107], v[106:107]
	v_pk_mul_f32 v[96:97], v[96:97], v[98:99] op_sel_hi:[1,0]
	v_pk_mul_f32 v[94:95], v[94:95], v[98:99] op_sel_hi:[1,0]
	v_pk_mul_f32 v[90:91], v[90:91], v[98:99] op_sel_hi:[1,0]
	v_pk_mul_f32 v[18:19], v[18:19], v[18:19]
	v_cvt_pk_bf16_f32 v129, v122, v123
	global_store_dwordx4 v[142:143], v[126:129], off offset:0 sc1
	s_nop 1
	v_lshl_add_u64 v[116:117], s[18:19], 0, v[116:117]
	v_cvt_pk_bf16_f32 v110, v110, v111
	v_cvt_pk_bf16_f32 v111, v112, v113
	v_cvt_pk_bf16_f32 v112, v106, v107
	v_max_f32_e32 v106, 0, v108
	v_max_f32_e32 v107, 0, v109
	v_max_f32_e32 v94, 0, v94
	v_max_f32_e32 v95, 0, v95
	v_max_f32_e32 v96, 0, v96
	v_max_f32_e32 v97, 0, v97
	v_max_f32_e32 v90, 0, v90
	v_max_f32_e32 v91, 0, v91
	v_cvt_pk_bf16_f32 v25, v18, v19
	v_fmamk_f32 v18, v154, 0x3a800000, v233
	global_store_dwordx4 v[142:143], v[118:121], off offset:0x100 sc1
	s_nop 1
	v_lshl_add_u64 v[116:117], v[116:117], 0, s[30:31]
	v_pk_mul_f32 v[106:107], v[106:107], v[106:107]
	v_lshlrev_b64 v[100:101], 13, v[146:147]
	v_pk_mul_f32 v[94:95], v[94:95], v[94:95]
	v_pk_mul_f32 v[96:97], v[96:97], v[96:97]
	v_pk_mul_f32 v[92:93], v[92:93], v[98:99] op_sel_hi:[1,0]
	v_pk_mul_f32 v[90:91], v[90:91], v[90:91]
	v_pk_mul_f32 v[80:81], v[80:81], v[82:83] op_sel_hi:[1,0]
	v_pk_mul_f32 v[78:79], v[78:79], v[82:83] op_sel_hi:[1,0]
	v_pk_mul_f32 v[74:75], v[74:75], v[82:83] op_sel_hi:[1,0]
	v_cmp_gt_f32_e32 vcc, s82, v18
	v_mul_f32_e32 v19, 0x4b800000, v18
	v_lshl_add_u64 v[116:117], v[116:117], 0, v[0:1]
	v_cvt_pk_bf16_f32 v113, v106, v107
	global_store_dwordx4 v[116:117], v[110:113], off offset:0 sc1
	s_nop 1
	v_lshl_add_u64 v[100:101], s[18:19], 0, v[100:101]
	v_cvt_pk_bf16_f32 v94, v94, v95
	v_cvt_pk_bf16_f32 v95, v96, v97
	v_cvt_pk_bf16_f32 v96, v90, v91
	v_max_f32_e32 v90, 0, v92
	v_max_f32_e32 v91, 0, v93
	v_max_f32_e32 v78, 0, v78
	v_max_f32_e32 v79, 0, v79
	v_max_f32_e32 v80, 0, v80
	v_max_f32_e32 v81, 0, v81
	v_max_f32_e32 v74, 0, v74
	v_max_f32_e32 v75, 0, v75
	v_cndmask_b32_e32 v18, v18, v19, vcc
	global_store_dwordx4 v[116:117], v[102:105], off offset:0x100 sc1
	s_nop 1
	v_lshl_add_u64 v[100:101], v[100:101], 0, s[30:31]
	v_pk_mul_f32 v[90:91], v[90:91], v[90:91]
	v_lshlrev_b64 v[84:85], 13, v[144:145]
	v_pk_mul_f32 v[78:79], v[78:79], v[78:79]
	v_pk_mul_f32 v[80:81], v[80:81], v[80:81]
	v_pk_mul_f32 v[76:77], v[76:77], v[82:83] op_sel_hi:[1,0]
	v_pk_mul_f32 v[74:75], v[74:75], v[74:75]
	v_pk_mul_f32 v[64:65], v[64:65], v[66:67] op_sel_hi:[1,0]
	v_pk_mul_f32 v[62:63], v[62:63], v[66:67] op_sel_hi:[1,0]
	v_pk_mul_f32 v[58:59], v[58:59], v[66:67] op_sel_hi:[1,0]
	v_rsq_f32_e32 v18, v18
	v_lshl_add_u64 v[100:101], v[100:101], 0, v[0:1]
	v_cvt_pk_bf16_f32 v97, v90, v91
	global_store_dwordx4 v[100:101], v[94:97], off offset:0 sc1
	s_nop 1
	v_lshl_add_u64 v[84:85], s[18:19], 0, v[84:85]
	v_cvt_pk_bf16_f32 v78, v78, v79
	v_cvt_pk_bf16_f32 v79, v80, v81
	v_cvt_pk_bf16_f32 v80, v74, v75
	v_max_f32_e32 v74, 0, v76
	v_max_f32_e32 v75, 0, v77
	v_max_f32_e32 v62, 0, v62
	v_max_f32_e32 v63, 0, v63
	v_max_f32_e32 v64, 0, v64
	v_max_f32_e32 v65, 0, v65
	v_max_f32_e32 v58, 0, v58
	v_max_f32_e32 v59, 0, v59
	global_store_dwordx4 v[100:101], v[86:89], off offset:0x100 sc1
	s_nop 1
	v_lshl_add_u64 v[84:85], v[84:85], 0, s[30:31]
	v_pk_mul_f32 v[74:75], v[74:75], v[74:75]
	v_pk_mul_f32 v[62:63], v[62:63], v[62:63]
	v_pk_mul_f32 v[64:65], v[64:65], v[64:65]
	v_pk_mul_f32 v[60:61], v[60:61], v[66:67] op_sel_hi:[1,0]
	v_pk_mul_f32 v[58:59], v[58:59], v[58:59]
	v_pk_mul_f32 v[48:49], v[48:49], v[50:51] op_sel_hi:[1,0]
	v_pk_mul_f32 v[46:47], v[46:47], v[50:51] op_sel_hi:[1,0]
	v_pk_mul_f32 v[42:43], v[42:43], v[50:51] op_sel_hi:[1,0]
	v_lshl_add_u64 v[84:85], v[84:85], 0, v[0:1]
	v_cvt_pk_bf16_f32 v81, v74, v75
	global_store_dwordx4 v[84:85], v[78:81], off offset:0 sc1
	s_nop 1
	v_cvt_pk_bf16_f32 v62, v62, v63
	v_cvt_pk_bf16_f32 v63, v64, v65
	v_cvt_pk_bf16_f32 v64, v58, v59
	v_max_f32_e32 v58, 0, v60
	v_max_f32_e32 v59, 0, v61
	v_max_f32_e32 v46, 0, v46
	v_max_f32_e32 v47, 0, v47
	v_max_f32_e32 v48, 0, v48
	v_max_f32_e32 v49, 0, v49
	v_max_f32_e32 v42, 0, v42
	v_max_f32_e32 v43, 0, v43
	global_store_dwordx4 v[84:85], v[70:73], off offset:0x100 sc1
	s_nop 1
	s_mov_b64 s[30:31], 0x100000
	v_pk_mul_f32 v[58:59], v[58:59], v[58:59]
	v_pk_mul_f32 v[46:47], v[46:47], v[46:47]
	v_pk_mul_f32 v[48:49], v[48:49], v[48:49]
	v_pk_mul_f32 v[44:45], v[44:45], v[50:51] op_sel_hi:[1,0]
	v_pk_mul_f32 v[42:43], v[42:43], v[42:43]
	v_pk_mul_f32 v[32:33], v[32:33], v[34:35] op_sel_hi:[1,0]
	v_pk_mul_f32 v[30:31], v[30:31], v[34:35] op_sel_hi:[1,0]
	v_pk_mul_f32 v[26:27], v[26:27], v[34:35] op_sel_hi:[1,0]
	v_mul_f32_e32 v19, 0x45800000, v18
	v_lshl_add_u64 v[68:69], v[142:143], 0, s[30:31]
	v_cvt_pk_bf16_f32 v65, v58, v59
	global_store_dwordx4 v[68:69], v[62:65], off offset:0 sc1
	s_nop 1
	v_cvt_pk_bf16_f32 v46, v46, v47
	v_cvt_pk_bf16_f32 v47, v48, v49
	v_cvt_pk_bf16_f32 v48, v42, v43
	v_max_f32_e32 v42, 0, v44
	v_max_f32_e32 v43, 0, v45
	v_max_f32_e32 v30, 0, v30
	v_max_f32_e32 v31, 0, v31
	v_max_f32_e32 v32, 0, v32
	v_max_f32_e32 v33, 0, v33
	v_max_f32_e32 v26, 0, v26
	v_max_f32_e32 v27, 0, v27
	v_cndmask_b32_e32 v18, v18, v19, vcc
	global_store_dwordx4 v[68:69], v[54:57], off offset:0x100 sc1
	s_nop 1
	s_mov_b64 s[30:31], 0x120000
	v_pk_mul_f32 v[42:43], v[42:43], v[42:43]
	v_pk_mul_f32 v[30:31], v[30:31], v[30:31]
	v_pk_mul_f32 v[32:33], v[32:33], v[32:33]
	v_pk_mul_f32 v[28:29], v[28:29], v[34:35] op_sel_hi:[1,0]
	v_pk_mul_f32 v[26:27], v[26:27], v[26:27]
	v_pk_mul_f32 v[16:17], v[16:17], v[18:19] op_sel_hi:[1,0]
	v_pk_mul_f32 v[14:15], v[14:15], v[18:19] op_sel_hi:[1,0]
	v_pk_mul_f32 v[10:11], v[10:11], v[18:19] op_sel_hi:[1,0]
	v_lshl_add_u64 v[52:53], v[142:143], 0, s[30:31]
	v_cvt_pk_bf16_f32 v49, v42, v43
	global_store_dwordx4 v[52:53], v[46:49], off offset:0 sc1
	s_nop 1
	v_cvt_pk_bf16_f32 v30, v30, v31
	v_cvt_pk_bf16_f32 v31, v32, v33
	v_cvt_pk_bf16_f32 v32, v26, v27
	v_max_f32_e32 v26, 0, v28
	v_max_f32_e32 v27, 0, v29
	v_max_f32_e32 v14, 0, v14
	v_max_f32_e32 v15, 0, v15
	v_max_f32_e32 v16, 0, v16
	v_max_f32_e32 v17, 0, v17
	v_max_f32_e32 v10, 0, v10
	v_max_f32_e32 v11, 0, v11
	v_pk_mul_f32 v[8:9], v[8:9], v[18:19] op_sel_hi:[1,0]
	v_pk_mul_f32 v[6:7], v[6:7], v[18:19] op_sel_hi:[1,0]
	v_pk_mul_f32 v[2:3], v[2:3], v[18:19] op_sel_hi:[1,0]
	global_store_dwordx4 v[52:53], v[38:41], off offset:0x100 sc1
	s_nop 1
	s_mov_b64 s[30:31], 0x140000
	v_pk_mul_f32 v[26:27], v[26:27], v[26:27]
	v_pk_mul_f32 v[14:15], v[14:15], v[14:15]
	v_pk_mul_f32 v[16:17], v[16:17], v[16:17]
	v_pk_mul_f32 v[12:13], v[12:13], v[18:19] op_sel_hi:[1,0]
	v_pk_mul_f32 v[10:11], v[10:11], v[10:11]
	v_max_f32_e32 v6, 0, v6
	v_max_f32_e32 v7, 0, v7
	v_max_f32_e32 v8, 0, v8
	v_max_f32_e32 v9, 0, v9
	v_max_f32_e32 v2, 0, v2
	v_max_f32_e32 v3, 0, v3
	v_lshl_add_u64 v[36:37], v[142:143], 0, s[30:31]
	v_cvt_pk_bf16_f32 v33, v26, v27
	global_store_dwordx4 v[36:37], v[30:33], off offset:0 sc1
	s_nop 1
	v_cvt_pk_bf16_f32 v14, v14, v15
	v_cvt_pk_bf16_f32 v15, v16, v17
	v_cvt_pk_bf16_f32 v16, v10, v11
	v_max_f32_e32 v10, 0, v12
	v_max_f32_e32 v11, 0, v13
	v_pk_mul_f32 v[6:7], v[6:7], v[6:7]
	v_pk_mul_f32 v[8:9], v[8:9], v[8:9]
	v_pk_mul_f32 v[4:5], v[4:5], v[18:19] op_sel_hi:[1,0]
	v_pk_mul_f32 v[2:3], v[2:3], v[2:3]
	global_store_dwordx4 v[36:37], v[22:25], off offset:0x100 sc1
	s_nop 1
	s_mov_b64 s[30:31], 0x160000
	v_pk_mul_f32 v[10:11], v[10:11], v[10:11]
	v_cvt_pk_bf16_f32 v6, v6, v7
	v_cvt_pk_bf16_f32 v7, v8, v9
	v_cvt_pk_bf16_f32 v8, v2, v3
	v_max_f32_e32 v2, 0, v4
	v_max_f32_e32 v3, 0, v5
	v_lshl_add_u64 v[20:21], v[142:143], 0, s[30:31]
	v_cvt_pk_bf16_f32 v17, v10, v11
	global_store_dwordx4 v[20:21], v[14:17], off offset:0 sc1
	s_nop 1
	v_pk_mul_f32 v[2:3], v[2:3], v[2:3]
	s_mov_b64 s[30:31], -1
	v_cvt_pk_bf16_f32 v9, v2, v3
	global_store_dwordx4 v[20:21], v[6:9], off offset:0x100 sc1
	s_nop 1
	s_andn2_b64 vcc, exec, s[8:9]
	s_cbranch_vccnz .LBB0_853
	s_andn2_b64 vcc, exec, s[16:17]
	s_cbranch_vccnz .LBB0_852
	s_barrier
	s_branch .LBB0_852
